# v51 with conservative vmcnt waits in the norm loop (count only younger loads, so correctness does not depend on store retirement order)
# baseline (speedup 1.0000x reference)
; __device__ __forceinline__ f32x4 bf4_to_f32(u32x2 w) { return (f32x4){__builtin_bit_cast(float, w.x << 16), __builtin_bit_cast(float, w.x & 0xffff0000u), __builtin_bit_cast(float, w.y << 16), __builtin_bit_cast(float, w.y & 0xffff0000u)}; }
; __device__ __forceinline__ void norm_phase(const Params& P, unsigned char* ws, int layer, int which, int nrows, bool first, int lane, int wave, const float* pend_part, int pend_ns, const float* pend_gate) {
;     ...
;     for (int row0 = gw; row0 < MLAT; row0 += NR * NGW) {
;         f32x4 v[NR][2][2]; float ss[NR];
; #pragma unroll
;         for (int r = 0; r < NR; ++r) { const int row = row0 + r * NGW; ss[r] = 0.f;
; #pragma unroll
;             for (int j = 0; j < 2; ++j) { const int col = 8 * lane + 512 * j;
;                 if (first) { v[r][j][0] = *(const f32x4*)(P.in[I_X] + (size_t)row * DM + col); v[r][j][1] = *(const f32x4*)(P.in[I_X] + (size_t)row * DM + col + 4); }
;                 else { const u32x4 w = *(const u32x4*)(XB + (size_t)row * DM + col); v[r][j][0] = bf4_to_f32((u32x2){w.x, w.y}); v[r][j][1] = bf4_to_f32((u32x2){w.z, w.w}); } } }
; #pragma unroll
;         for (int r = 0; r < NR; ++r)
; #pragma unroll
;             for (int j = 0; j < 2; ++j)
; #pragma unroll
;                 for (int q = 0; q < 2; ++q) ss[r] += (v[r][j][q][0] * v[r][j][q][0] + v[r][j][q][1] * v[r][j][q][1]) + (v[r][j][q][2] * v[r][j][q][2] + v[r][j][q][3] * v[r][j][q][3]);
; #pragma unroll
;         for (int r = 0; r < NR; ++r) { const int row = row0 + r * NGW;
;             const float rstd = rsqrtf(wave_sum(ss[r], lane) * (1.0f / DM) + EPS);
;             const float* mod = (const float*)(ws + WS_MOD) + (size_t)(layer * 9 + (row >> 12)) * 6144 + which * 3 * DM;
; #pragma unroll
;             for (int j = 0; j < 2; ++j) { const int col = 8 * lane + 512 * j; u32x4 hw, xw;
; #pragma unroll
;                 for (int q = 0; q < 2; ++q) {
;                     const f32x4 g4 = *(const f32x4*)(g + col + 4 * q), sh = *(const f32x4*)(mod + col + 4 * q), sc = *(const f32x4*)(mod + DM + col + 4 * q);
.Lmy_norm_entry:
	s_waitcnt vmcnt(0) lgkmcnt(0)
	v_readlane_b32 s48, v251, 10
	v_readlane_b32 s49, v251, 11
	v_readlane_b32 s50, v251, 12
	v_readlane_b32 s51, v251, 13
	v_readlane_b32 s52, v251, 14
	v_readlane_b32 s53, v251, 15
	v_readlane_b32 s54, v251, 16
	v_readlane_b32 s55, v251, 17
	v_readlane_b32 s56, v251, 18
	v_readlane_b32 s57, v251, 19
	v_readlane_b32 s58, v251, 20
	v_readlane_b32 s59, v251, 21
	v_readlane_b32 s60, v251, 22
	v_readlane_b32 s61, v251, 23
	v_readlane_b32 s62, v251, 24
	v_readlane_b32 s63, v251, 25
	s_add_u32 s22, s62, 0x4000000
	s_addc_u32 s23, s63, 0
	s_add_u32 s26, s20, 0x6400000
	s_addc_u32 s27, s21, 0
	v_lshlrev_b32_e32 v2, 4, v221
	v_lshlrev_b32_e32 v3, 5, v221
	v_lshlrev_b32_e32 v0, 2, v221
	s_lshl_b32 s98, s2, 4
	s_lshr_b32 s10, s2, 8
	s_lshl_b32 s10, s10, 12
	v_add_u32_e32 v15, s10, v3
	v_xor_b32_e32 v5, 4, v0
	v_xor_b32_e32 v6, 8, v0
	v_xor_b32_e32 v7, 16, v0
	v_xor_b32_e32 v9, 32, v0
	v_xor_b32_e32 v10, 64, v0
	v_xor_b32_e32 v11, 0x80, v0
	s_lshr_b32 s10, s2, 8
	s_add_i32 s10, s10, s12
	s_mul_hi_i32 s13, s10, 0x6000
	s_mulk_i32 s10, 0x6000
	s_add_u32 s0, s8, s10
	s_addc_u32 s1, s9, s13
	s_add_u32 s30, s0, 0x1000
	s_addc_u32 s31, s1, 0
	global_load_dwordx4 v[32:35], v3, s[0:1]
	global_load_dwordx4 v[36:39], v3, s[0:1] offset:16
	global_load_dwordx4 v[40:43], v3, s[0:1] offset:2048
	global_load_dwordx4 v[44:47], v3, s[0:1] offset:2064
	global_load_dwordx4 v[48:51], v3, s[30:31]
	global_load_dwordx4 v[52:55], v3, s[30:31] offset:16
	global_load_dwordx4 v[56:59], v3, s[30:31] offset:2048
	global_load_dwordx4 v[60:63], v3, s[30:31] offset:2064
	global_load_dwordx4 v[16:19], v3, s[24:25]
	global_load_dwordx4 v[20:23], v3, s[24:25] offset:16
	global_load_dwordx4 v[24:27], v3, s[24:25] offset:2048
	global_load_dwordx4 v[28:31], v3, s[24:25] offset:2064
	s_mov_b32 s10, s98
	s_lshl_b32 s10, s10, 11
	s_add_u32 s28, s22, s10
	s_addc_u32 s29, s23, 0
	global_load_dwordx4 v[64:67], v2, s[28:29]
	global_load_dwordx4 v[68:71], v2, s[28:29] offset:1024
	s_add_i32 s10, s98, 0x1
	s_lshl_b32 s10, s10, 11
	s_add_u32 s28, s22, s10
	s_addc_u32 s29, s23, 0
	global_load_dwordx4 v[72:75], v2, s[28:29]
	global_load_dwordx4 v[76:79], v2, s[28:29] offset:1024
	s_add_i32 s10, s98, 0x2
	s_lshl_b32 s10, s10, 11
	s_add_u32 s28, s22, s10
	s_addc_u32 s29, s23, 0
	global_load_dwordx4 v[80:83], v2, s[28:29]
	global_load_dwordx4 v[84:87], v2, s[28:29] offset:1024
	s_add_i32 s10, s98, 0x3
	s_lshl_b32 s10, s10, 11
	s_add_u32 s28, s22, s10
	s_addc_u32 s29, s23, 0
	global_load_dwordx4 v[88:91], v2, s[28:29]
	global_load_dwordx4 v[92:95], v2, s[28:29] offset:1024
	s_add_i32 s10, s98, 0x4
	s_lshl_b32 s10, s10, 11
	s_add_u32 s28, s22, s10
	s_addc_u32 s29, s23, 0
	global_load_dwordx4 v[96:99], v2, s[28:29]
	global_load_dwordx4 v[100:103], v2, s[28:29] offset:1024
	s_add_i32 s10, s98, 0x5
	s_lshl_b32 s10, s10, 11
	s_add_u32 s28, s22, s10
	s_addc_u32 s29, s23, 0
	global_load_dwordx4 v[104:107], v2, s[28:29]
	global_load_dwordx4 v[108:111], v2, s[28:29] offset:1024
	s_add_i32 s10, s98, 0x6
	s_lshl_b32 s10, s10, 11
	s_add_u32 s28, s22, s10
	s_addc_u32 s29, s23, 0
	global_load_dwordx4 v[112:115], v2, s[28:29]
	global_load_dwordx4 v[116:119], v2, s[28:29] offset:1024
	s_add_i32 s10, s98, 0x7
	s_lshl_b32 s10, s10, 11
	s_add_u32 s28, s22, s10
	s_addc_u32 s29, s23, 0
	global_load_dwordx4 v[120:123], v2, s[28:29]
	global_load_dwordx4 v[124:127], v2, s[28:29] offset:1024
	s_waitcnt vmcnt(12)
	v_lshlrev_b32_e32 v128, 16, v64
	v_and_b32_e32 v129, 0xffff0000, v64
	v_lshlrev_b32_e32 v130, 16, v65
	v_and_b32_e32 v131, 0xffff0000, v65
	v_lshlrev_b32_e32 v132, 16, v66
	v_and_b32_e32 v133, 0xffff0000, v66
	v_lshlrev_b32_e32 v134, 16, v67
	v_and_b32_e32 v135, 0xffff0000, v67
	v_lshlrev_b32_e32 v136, 16, v68
	v_and_b32_e32 v137, 0xffff0000, v68
	v_lshlrev_b32_e32 v138, 16, v69
	v_and_b32_e32 v139, 0xffff0000, v69
	v_lshlrev_b32_e32 v140, 16, v70
	v_and_b32_e32 v141, 0xffff0000, v70
	v_lshlrev_b32_e32 v142, 16, v71
	v_and_b32_e32 v143, 0xffff0000, v71
	v_lshlrev_b32_e32 v144, 16, v72
	v_and_b32_e32 v145, 0xffff0000, v72
	v_lshlrev_b32_e32 v146, 16, v73
	v_and_b32_e32 v147, 0xffff0000, v73
	v_lshlrev_b32_e32 v148, 16, v74
	v_and_b32_e32 v149, 0xffff0000, v74
	v_lshlrev_b32_e32 v150, 16, v75
	v_and_b32_e32 v151, 0xffff0000, v75
	v_lshlrev_b32_e32 v152, 16, v76
	v_and_b32_e32 v153, 0xffff0000, v76
	v_lshlrev_b32_e32 v154, 16, v77
	v_and_b32_e32 v155, 0xffff0000, v77
	v_lshlrev_b32_e32 v156, 16, v78
	v_and_b32_e32 v157, 0xffff0000, v78
	v_lshlrev_b32_e32 v158, 16, v79
	v_and_b32_e32 v159, 0xffff0000, v79
	v_pk_mul_f32 v[160:161], v[128:129], v[128:129]
	v_pk_mul_f32 v[162:163], v[144:145], v[144:145]
	v_pk_fma_f32 v[160:161], v[130:131], v[130:131], v[160:161]
	v_pk_fma_f32 v[162:163], v[146:147], v[146:147], v[162:163]
	v_pk_fma_f32 v[160:161], v[132:133], v[132:133], v[160:161]
	v_pk_fma_f32 v[162:163], v[148:149], v[148:149], v[162:163]
	v_pk_fma_f32 v[160:161], v[134:135], v[134:135], v[160:161]
	v_pk_fma_f32 v[162:163], v[150:151], v[150:151], v[162:163]
	v_pk_fma_f32 v[160:161], v[136:137], v[136:137], v[160:161]
	v_pk_fma_f32 v[162:163], v[152:153], v[152:153], v[162:163]
	v_pk_fma_f32 v[160:161], v[138:139], v[138:139], v[160:161]
	v_pk_fma_f32 v[162:163], v[154:155], v[154:155], v[162:163]
	v_pk_fma_f32 v[160:161], v[140:141], v[140:141], v[160:161]
	v_pk_fma_f32 v[162:163], v[156:157], v[156:157], v[162:163]
	v_pk_fma_f32 v[160:161], v[142:143], v[142:143], v[160:161]
	v_pk_fma_f32 v[162:163], v[158:159], v[158:159], v[162:163]
	v_add_f32_e32 v160, v160, v161
	v_add_f32_e32 v162, v162, v163
	ds_bpermute_b32 v164, v5, v160
	ds_bpermute_b32 v165, v5, v162
	s_waitcnt lgkmcnt(0)
; __device__ __forceinline__ unsigned cvt_pk_bf16(float lo, float hi) { unsigned r; asm volatile("v_cvt_pk_bf16_f32 %0, %1, %2" : "=v"(r) : "v"(lo), "v"(hi)); return r; }
; __device__ __forceinline__ void norm_phase(const Params& P, unsigned char* ws, int layer, int which, int nrows, bool first, int lane, int wave, const float* pend_part, int pend_ns, const float* pend_gate) {
;     ...
; #pragma unroll
;         for (int r = 0; r < NR; ++r) { const int row = row0 + r * NGW;
;             const float rstd = rsqrtf(wave_sum(ss[r], lane) * (1.0f / DM) + EPS);
;             const float* mod = (const float*)(ws + WS_MOD) + (size_t)(layer * 9 + (row >> 12)) * 6144 + which * 3 * DM;
; #pragma unroll
;             for (int j = 0; j < 2; ++j) { const int col = 8 * lane + 512 * j; u32x4 hw, xw;
; #pragma unroll
;                 for (int q = 0; q < 2; ++q) {
;                     const f32x4 g4 = *(const f32x4*)(g + col + 4 * q), sh = *(const f32x4*)(mod + col + 4 * q), sc = *(const f32x4*)(mod + DM + col + 4 * q);
;                     const f32x4 h = (v[r][j][q] * rstd) * g4 * (sc + 1.0f) + sh;
;                     if (q == 0) { hw.x = cvt_pk_bf16(h[0], h[1]); hw.y = cvt_pk_bf16(h[2], h[3]); xw.x = cvt_pk_bf16(v[r][j][q][0], v[r][j][q][1]); xw.y = cvt_pk_bf16(v[r][j][q][2], v[r][j][q][3]); }
;                     else { hw.z = cvt_pk_bf16(h[0], h[1]); hw.w = cvt_pk_bf16(h[2], h[3]); xw.z = cvt_pk_bf16(v[r][j][q][0], v[r][j][q][1]); xw.w = cvt_pk_bf16(v[r][j][q][2], v[r][j][q][3]); }
;                 }
;                 *(u32x4*)(H + (size_t)row * DM + col) = hw;
;                 if (first) *(u32x4*)(XB + (size_t)row * DM + col) = xw;
;             } }
	v_add_f32_e32 v160, v160, v164
	v_add_f32_e32 v162, v162, v165
	ds_bpermute_b32 v164, v6, v160
	ds_bpermute_b32 v165, v6, v162
	s_waitcnt lgkmcnt(0)
	v_add_f32_e32 v160, v160, v164
	v_add_f32_e32 v162, v162, v165
	ds_bpermute_b32 v164, v7, v160
	ds_bpermute_b32 v165, v7, v162
	s_waitcnt lgkmcnt(0)
	v_add_f32_e32 v160, v160, v164
	v_add_f32_e32 v162, v162, v165
	ds_bpermute_b32 v164, v9, v160
	ds_bpermute_b32 v165, v9, v162
	s_waitcnt lgkmcnt(0)
	v_add_f32_e32 v160, v160, v164
	v_add_f32_e32 v162, v162, v165
	ds_bpermute_b32 v164, v10, v160
	ds_bpermute_b32 v165, v10, v162
	s_waitcnt lgkmcnt(0)
	v_add_f32_e32 v160, v160, v164
	v_add_f32_e32 v162, v162, v165
	ds_bpermute_b32 v164, v11, v160
	ds_bpermute_b32 v165, v11, v162
	s_waitcnt lgkmcnt(0)
	v_add_f32_e32 v160, v160, v164
	v_add_f32_e32 v162, v162, v165
	v_fmamk_f32 v160, v160, 0x3a800000, v194
	v_fmamk_f32 v162, v162, 0x3a800000, v194
	v_rsq_f32_e32 v160, v160
	v_rsq_f32_e32 v162, v162
	v_pk_add_f32 v[48:49], v[48:49], 1.0 op_sel_hi:[1,0]
	v_pk_add_f32 v[50:51], v[50:51], 1.0 op_sel_hi:[1,0]
	v_pk_add_f32 v[52:53], v[52:53], 1.0 op_sel_hi:[1,0]
	v_pk_add_f32 v[54:55], v[54:55], 1.0 op_sel_hi:[1,0]
	v_pk_add_f32 v[56:57], v[56:57], 1.0 op_sel_hi:[1,0]
	v_pk_add_f32 v[58:59], v[58:59], 1.0 op_sel_hi:[1,0]
	v_pk_add_f32 v[60:61], v[60:61], 1.0 op_sel_hi:[1,0]
	v_pk_add_f32 v[62:63], v[62:63], 1.0 op_sel_hi:[1,0]
	v_pk_mul_f32 v[128:129], v[160:161], v[128:129] op_sel_hi:[0,1]
	v_pk_mul_f32 v[130:131], v[160:161], v[130:131] op_sel_hi:[0,1]
	v_pk_mul_f32 v[132:133], v[160:161], v[132:133] op_sel_hi:[0,1]
	v_pk_mul_f32 v[134:135], v[160:161], v[134:135] op_sel_hi:[0,1]
	v_pk_mul_f32 v[136:137], v[160:161], v[136:137] op_sel_hi:[0,1]
	v_pk_mul_f32 v[138:139], v[160:161], v[138:139] op_sel_hi:[0,1]
	v_pk_mul_f32 v[140:141], v[160:161], v[140:141] op_sel_hi:[0,1]
	v_pk_mul_f32 v[142:143], v[160:161], v[142:143] op_sel_hi:[0,1]
	v_pk_mul_f32 v[128:129], v[16:17], v[128:129]
	v_pk_mul_f32 v[130:131], v[18:19], v[130:131]
	v_pk_mul_f32 v[132:133], v[20:21], v[132:133]
	v_pk_mul_f32 v[134:135], v[22:23], v[134:135]
	v_pk_mul_f32 v[136:137], v[24:25], v[136:137]
	v_pk_mul_f32 v[138:139], v[26:27], v[138:139]
	v_pk_mul_f32 v[140:141], v[28:29], v[140:141]
	v_pk_mul_f32 v[142:143], v[30:31], v[142:143]
	v_pk_fma_f32 v[128:129], v[48:49], v[128:129], v[32:33]
	v_pk_fma_f32 v[130:131], v[50:51], v[130:131], v[34:35]
	v_pk_fma_f32 v[132:133], v[52:53], v[132:133], v[36:37]
	v_pk_fma_f32 v[134:135], v[54:55], v[134:135], v[38:39]
	v_pk_fma_f32 v[136:137], v[56:57], v[136:137], v[40:41]
	v_pk_fma_f32 v[138:139], v[58:59], v[138:139], v[42:43]
	v_pk_fma_f32 v[140:141], v[60:61], v[140:141], v[44:45]
	v_pk_fma_f32 v[142:143], v[62:63], v[142:143], v[46:47]
	v_cvt_pk_bf16_f32 v176, v128, v129
	v_cvt_pk_bf16_f32 v177, v130, v131
	v_cvt_pk_bf16_f32 v178, v132, v133
	v_cvt_pk_bf16_f32 v179, v134, v135
	v_cvt_pk_bf16_f32 v180, v136, v137
	v_cvt_pk_bf16_f32 v181, v138, v139
	v_cvt_pk_bf16_f32 v182, v140, v141
	v_cvt_pk_bf16_f32 v183, v142, v143
	s_mov_b32 s10, s98
	s_lshl_b32 s10, s10, 11
	s_add_u32 s28, s26, s10
	s_addc_u32 s29, s27, 0
	global_store_dwordx4 v2, v[176:179], s[28:29] sc1
	global_store_dwordx4 v2, v[180:183], s[28:29] offset:1024 sc1
	v_pk_mul_f32 v[144:145], v[162:163], v[144:145] op_sel_hi:[0,1]
	v_pk_mul_f32 v[146:147], v[162:163], v[146:147] op_sel_hi:[0,1]
	v_pk_mul_f32 v[148:149], v[162:163], v[148:149] op_sel_hi:[0,1]
	v_pk_mul_f32 v[150:151], v[162:163], v[150:151] op_sel_hi:[0,1]
	v_pk_mul_f32 v[152:153], v[162:163], v[152:153] op_sel_hi:[0,1]
	v_pk_mul_f32 v[154:155], v[162:163], v[154:155] op_sel_hi:[0,1]
	v_pk_mul_f32 v[156:157], v[162:163], v[156:157] op_sel_hi:[0,1]
	v_pk_mul_f32 v[158:159], v[162:163], v[158:159] op_sel_hi:[0,1]
	v_pk_mul_f32 v[144:145], v[16:17], v[144:145]
	v_pk_mul_f32 v[146:147], v[18:19], v[146:147]
	v_pk_mul_f32 v[148:149], v[20:21], v[148:149]
	v_pk_mul_f32 v[150:151], v[22:23], v[150:151]
	v_pk_mul_f32 v[152:153], v[24:25], v[152:153]
	v_pk_mul_f32 v[154:155], v[26:27], v[154:155]
	v_pk_mul_f32 v[156:157], v[28:29], v[156:157]
	v_pk_mul_f32 v[158:159], v[30:31], v[158:159]
	v_pk_fma_f32 v[144:145], v[48:49], v[144:145], v[32:33]
	v_pk_fma_f32 v[146:147], v[50:51], v[146:147], v[34:35]
	v_pk_fma_f32 v[148:149], v[52:53], v[148:149], v[36:37]
	v_pk_fma_f32 v[150:151], v[54:55], v[150:151], v[38:39]
	v_pk_fma_f32 v[152:153], v[56:57], v[152:153], v[40:41]
	v_pk_fma_f32 v[154:155], v[58:59], v[154:155], v[42:43]
	v_pk_fma_f32 v[156:157], v[60:61], v[156:157], v[44:45]
	v_pk_fma_f32 v[158:159], v[62:63], v[158:159], v[46:47]
	v_cvt_pk_bf16_f32 v184, v144, v145
	v_cvt_pk_bf16_f32 v185, v146, v147
	v_cvt_pk_bf16_f32 v186, v148, v149
	v_cvt_pk_bf16_f32 v187, v150, v151
	v_cvt_pk_bf16_f32 v188, v152, v153
	v_cvt_pk_bf16_f32 v189, v154, v155
	v_cvt_pk_bf16_f32 v190, v156, v157
	v_cvt_pk_bf16_f32 v191, v158, v159
	s_add_i32 s10, s98, 0x1
	s_lshl_b32 s10, s10, 11
	s_add_u32 s28, s26, s10
	s_addc_u32 s29, s27, 0
	global_store_dwordx4 v2, v[184:187], s[28:29] sc1
	global_store_dwordx4 v2, v[188:191], s[28:29] offset:1024 sc1
	s_add_i32 s10, s98, 0x8
	s_lshl_b32 s10, s10, 11
	s_add_u32 s28, s22, s10
	s_addc_u32 s29, s23, 0
	global_load_dwordx4 v[64:67], v2, s[28:29]
	global_load_dwordx4 v[68:71], v2, s[28:29] offset:1024
	s_add_i32 s10, s98, 0x9
	s_lshl_b32 s10, s10, 11
	s_add_u32 s28, s22, s10
	s_addc_u32 s29, s23, 0
	global_load_dwordx4 v[72:75], v2, s[28:29]
	global_load_dwordx4 v[76:79], v2, s[28:29] offset:1024
	s_waitcnt vmcnt(12)
; __device__ __forceinline__ unsigned cvt_pk_bf16(float lo, float hi) { unsigned r; asm volatile("v_cvt_pk_bf16_f32 %0, %1, %2" : "=v"(r) : "v"(lo), "v"(hi)); return r; }
; __device__ __forceinline__ void norm_phase(const Params& P, unsigned char* ws, int layer, int which, int nrows, bool first, int lane, int wave, const float* pend_part, int pend_ns, const float* pend_gate) {
;     ...
;             for (int j = 0; j < 2; ++j) { const int col = 8 * lane + 512 * j;
;                 if (first) { v[r][j][0] = *(const f32x4*)(P.in[I_X] + (size_t)row * DM + col); v[r][j][1] = *(const f32x4*)(P.in[I_X] + (size_t)row * DM + col + 4); }
;                 else { const u32x4 w = *(const u32x4*)(XB + (size_t)row * DM + col); v[r][j][0] = bf4_to_f32((u32x2){w.x, w.y}); v[r][j][1] = bf4_to_f32((u32x2){w.z, w.w}); } } }
; #pragma unroll
;         for (int r = 0; r < NR; ++r)
; #pragma unroll
;             for (int j = 0; j < 2; ++j)
; #pragma unroll
;                 for (int q = 0; q < 2; ++q) ss[r] += (v[r][j][q][0] * v[r][j][q][0] + v[r][j][q][1] * v[r][j][q][1]) + (v[r][j][q][2] * v[r][j][q][2] + v[r][j][q][3] * v[r][j][q][3]);
; #pragma unroll
;         for (int r = 0; r < NR; ++r) { const int row = row0 + r * NGW;
;             const float rstd = rsqrtf(wave_sum(ss[r], lane) * (1.0f / DM) + EPS);
;             const float* mod = (const float*)(ws + WS_MOD) + (size_t)(layer * 9 + (row >> 12)) * 6144 + which * 3 * DM;
; #pragma unroll
;             for (int j = 0; j < 2; ++j) { const int col = 8 * lane + 512 * j; u32x4 hw, xw;
; #pragma unroll
;                 for (int q = 0; q < 2; ++q) {
;                     const f32x4 g4 = *(const f32x4*)(g + col + 4 * q), sh = *(const f32x4*)(mod + col + 4 * q), sc = *(const f32x4*)(mod + DM + col + 4 * q);
;                     const f32x4 h = (v[r][j][q] * rstd) * g4 * (sc + 1.0f) + sh;
;                     if (q == 0) { hw.x = cvt_pk_bf16(h[0], h[1]); hw.y = cvt_pk_bf16(h[2], h[3]); xw.x = cvt_pk_bf16(v[r][j][q][0], v[r][j][q][1]); xw.y = cvt_pk_bf16(v[r][j][q][2], v[r][j][q][3]); }
;                     else { hw.z = cvt_pk_bf16(h[0], h[1]); hw.w = cvt_pk_bf16(h[2], h[3]); xw.z = cvt_pk_bf16(v[r][j][q][0], v[r][j][q][1]); xw.w = cvt_pk_bf16(v[r][j][q][2], v[r][j][q][3]); }
;                 }
;                 *(u32x4*)(H + (size_t)row * DM + col) = hw;
	v_lshlrev_b32_e32 v128, 16, v80
	v_and_b32_e32 v129, 0xffff0000, v80
	v_lshlrev_b32_e32 v130, 16, v81
	v_and_b32_e32 v131, 0xffff0000, v81
	v_lshlrev_b32_e32 v132, 16, v82
	v_and_b32_e32 v133, 0xffff0000, v82
	v_lshlrev_b32_e32 v134, 16, v83
	v_and_b32_e32 v135, 0xffff0000, v83
	v_lshlrev_b32_e32 v136, 16, v84
	v_and_b32_e32 v137, 0xffff0000, v84
	v_lshlrev_b32_e32 v138, 16, v85
	v_and_b32_e32 v139, 0xffff0000, v85
	v_lshlrev_b32_e32 v140, 16, v86
	v_and_b32_e32 v141, 0xffff0000, v86
	v_lshlrev_b32_e32 v142, 16, v87
	v_and_b32_e32 v143, 0xffff0000, v87
	v_lshlrev_b32_e32 v144, 16, v88
	v_and_b32_e32 v145, 0xffff0000, v88
	v_lshlrev_b32_e32 v146, 16, v89
	v_and_b32_e32 v147, 0xffff0000, v89
	v_lshlrev_b32_e32 v148, 16, v90
	v_and_b32_e32 v149, 0xffff0000, v90
	v_lshlrev_b32_e32 v150, 16, v91
	v_and_b32_e32 v151, 0xffff0000, v91
	v_lshlrev_b32_e32 v152, 16, v92
	v_and_b32_e32 v153, 0xffff0000, v92
	v_lshlrev_b32_e32 v154, 16, v93
	v_and_b32_e32 v155, 0xffff0000, v93
	v_lshlrev_b32_e32 v156, 16, v94
	v_and_b32_e32 v157, 0xffff0000, v94
	v_lshlrev_b32_e32 v158, 16, v95
	v_and_b32_e32 v159, 0xffff0000, v95
	v_pk_mul_f32 v[160:161], v[128:129], v[128:129]
	v_pk_mul_f32 v[162:163], v[144:145], v[144:145]
	v_pk_fma_f32 v[160:161], v[130:131], v[130:131], v[160:161]
	v_pk_fma_f32 v[162:163], v[146:147], v[146:147], v[162:163]
	v_pk_fma_f32 v[160:161], v[132:133], v[132:133], v[160:161]
	v_pk_fma_f32 v[162:163], v[148:149], v[148:149], v[162:163]
	v_pk_fma_f32 v[160:161], v[134:135], v[134:135], v[160:161]
	v_pk_fma_f32 v[162:163], v[150:151], v[150:151], v[162:163]
	v_pk_fma_f32 v[160:161], v[136:137], v[136:137], v[160:161]
	v_pk_fma_f32 v[162:163], v[152:153], v[152:153], v[162:163]
	v_pk_fma_f32 v[160:161], v[138:139], v[138:139], v[160:161]
	v_pk_fma_f32 v[162:163], v[154:155], v[154:155], v[162:163]
	v_pk_fma_f32 v[160:161], v[140:141], v[140:141], v[160:161]
	v_pk_fma_f32 v[162:163], v[156:157], v[156:157], v[162:163]
	v_pk_fma_f32 v[160:161], v[142:143], v[142:143], v[160:161]
	v_pk_fma_f32 v[162:163], v[158:159], v[158:159], v[162:163]
	v_add_f32_e32 v160, v160, v161
	v_add_f32_e32 v162, v162, v163
	ds_bpermute_b32 v164, v5, v160
	ds_bpermute_b32 v165, v5, v162
	s_waitcnt lgkmcnt(0)
	v_add_f32_e32 v160, v160, v164
	v_add_f32_e32 v162, v162, v165
	ds_bpermute_b32 v164, v6, v160
	ds_bpermute_b32 v165, v6, v162
	s_waitcnt lgkmcnt(0)
	v_add_f32_e32 v160, v160, v164
	v_add_f32_e32 v162, v162, v165
	ds_bpermute_b32 v164, v7, v160
	ds_bpermute_b32 v165, v7, v162
	s_waitcnt lgkmcnt(0)
	v_add_f32_e32 v160, v160, v164
	v_add_f32_e32 v162, v162, v165
	ds_bpermute_b32 v164, v9, v160
	ds_bpermute_b32 v165, v9, v162
	s_waitcnt lgkmcnt(0)
	v_add_f32_e32 v160, v160, v164
	v_add_f32_e32 v162, v162, v165
	ds_bpermute_b32 v164, v10, v160
	ds_bpermute_b32 v165, v10, v162
	s_waitcnt lgkmcnt(0)
	v_add_f32_e32 v160, v160, v164
	v_add_f32_e32 v162, v162, v165
	ds_bpermute_b32 v164, v11, v160
	ds_bpermute_b32 v165, v11, v162
	s_waitcnt lgkmcnt(0)
	v_add_f32_e32 v160, v160, v164
	v_add_f32_e32 v162, v162, v165
	v_fmamk_f32 v160, v160, 0x3a800000, v194
	v_fmamk_f32 v162, v162, 0x3a800000, v194
	v_rsq_f32_e32 v160, v160
	v_rsq_f32_e32 v162, v162
	s_nop 0
	v_pk_mul_f32 v[128:129], v[160:161], v[128:129] op_sel_hi:[0,1]
	v_pk_mul_f32 v[130:131], v[160:161], v[130:131] op_sel_hi:[0,1]
	v_pk_mul_f32 v[132:133], v[160:161], v[132:133] op_sel_hi:[0,1]
	v_pk_mul_f32 v[134:135], v[160:161], v[134:135] op_sel_hi:[0,1]
	v_pk_mul_f32 v[136:137], v[160:161], v[136:137] op_sel_hi:[0,1]
	v_pk_mul_f32 v[138:139], v[160:161], v[138:139] op_sel_hi:[0,1]
	v_pk_mul_f32 v[140:141], v[160:161], v[140:141] op_sel_hi:[0,1]
	v_pk_mul_f32 v[142:143], v[160:161], v[142:143] op_sel_hi:[0,1]
	v_pk_mul_f32 v[128:129], v[16:17], v[128:129]
	v_pk_mul_f32 v[130:131], v[18:19], v[130:131]
	v_pk_mul_f32 v[132:133], v[20:21], v[132:133]
	v_pk_mul_f32 v[134:135], v[22:23], v[134:135]
	v_pk_mul_f32 v[136:137], v[24:25], v[136:137]
	v_pk_mul_f32 v[138:139], v[26:27], v[138:139]
	v_pk_mul_f32 v[140:141], v[28:29], v[140:141]
	v_pk_mul_f32 v[142:143], v[30:31], v[142:143]
	v_pk_fma_f32 v[128:129], v[48:49], v[128:129], v[32:33]
	v_pk_fma_f32 v[130:131], v[50:51], v[130:131], v[34:35]
	v_pk_fma_f32 v[132:133], v[52:53], v[132:133], v[36:37]
	v_pk_fma_f32 v[134:135], v[54:55], v[134:135], v[38:39]
	v_pk_fma_f32 v[136:137], v[56:57], v[136:137], v[40:41]
	v_pk_fma_f32 v[138:139], v[58:59], v[138:139], v[42:43]
	v_pk_fma_f32 v[140:141], v[60:61], v[140:141], v[44:45]
	v_pk_fma_f32 v[142:143], v[62:63], v[142:143], v[46:47]
	v_cvt_pk_bf16_f32 v176, v128, v129
	v_cvt_pk_bf16_f32 v177, v130, v131
	v_cvt_pk_bf16_f32 v178, v132, v133
	v_cvt_pk_bf16_f32 v179, v134, v135
	v_cvt_pk_bf16_f32 v180, v136, v137
	v_cvt_pk_bf16_f32 v181, v138, v139
	v_cvt_pk_bf16_f32 v182, v140, v141
	v_cvt_pk_bf16_f32 v183, v142, v143
	s_add_i32 s10, s98, 0x2
	s_lshl_b32 s10, s10, 11
	s_add_u32 s28, s26, s10
	s_addc_u32 s29, s27, 0
	global_store_dwordx4 v2, v[176:179], s[28:29] sc1
	global_store_dwordx4 v2, v[180:183], s[28:29] offset:1024 sc1
	v_pk_mul_f32 v[144:145], v[162:163], v[144:145] op_sel_hi:[0,1]
	v_pk_mul_f32 v[146:147], v[162:163], v[146:147] op_sel_hi:[0,1]
	v_pk_mul_f32 v[148:149], v[162:163], v[148:149] op_sel_hi:[0,1]
	v_pk_mul_f32 v[150:151], v[162:163], v[150:151] op_sel_hi:[0,1]
	v_pk_mul_f32 v[152:153], v[162:163], v[152:153] op_sel_hi:[0,1]
	v_pk_mul_f32 v[154:155], v[162:163], v[154:155] op_sel_hi:[0,1]
	v_pk_mul_f32 v[156:157], v[162:163], v[156:157] op_sel_hi:[0,1]
	v_pk_mul_f32 v[158:159], v[162:163], v[158:159] op_sel_hi:[0,1]
	v_pk_mul_f32 v[144:145], v[16:17], v[144:145]
	v_pk_mul_f32 v[146:147], v[18:19], v[146:147]
; __device__ __forceinline__ unsigned cvt_pk_bf16(float lo, float hi) { unsigned r; asm volatile("v_cvt_pk_bf16_f32 %0, %1, %2" : "=v"(r) : "v"(lo), "v"(hi)); return r; }
; __device__ __forceinline__ void norm_phase(const Params& P, unsigned char* ws, int layer, int which, int nrows, bool first, int lane, int wave, const float* pend_part, int pend_ns, const float* pend_gate) {
;     ...
;             for (int j = 0; j < 2; ++j) { const int col = 8 * lane + 512 * j;
;                 if (first) { v[r][j][0] = *(const f32x4*)(P.in[I_X] + (size_t)row * DM + col); v[r][j][1] = *(const f32x4*)(P.in[I_X] + (size_t)row * DM + col + 4); }
;                 else { const u32x4 w = *(const u32x4*)(XB + (size_t)row * DM + col); v[r][j][0] = bf4_to_f32((u32x2){w.x, w.y}); v[r][j][1] = bf4_to_f32((u32x2){w.z, w.w}); } } }
; #pragma unroll
;         for (int r = 0; r < NR; ++r)
; #pragma unroll
;             for (int j = 0; j < 2; ++j)
; #pragma unroll
;                 for (int q = 0; q < 2; ++q) ss[r] += (v[r][j][q][0] * v[r][j][q][0] + v[r][j][q][1] * v[r][j][q][1]) + (v[r][j][q][2] * v[r][j][q][2] + v[r][j][q][3] * v[r][j][q][3]);
; #pragma unroll
;         for (int r = 0; r < NR; ++r) { const int row = row0 + r * NGW;
;             const float rstd = rsqrtf(wave_sum(ss[r], lane) * (1.0f / DM) + EPS);
;             const float* mod = (const float*)(ws + WS_MOD) + (size_t)(layer * 9 + (row >> 12)) * 6144 + which * 3 * DM;
; #pragma unroll
;             for (int j = 0; j < 2; ++j) { const int col = 8 * lane + 512 * j; u32x4 hw, xw;
; #pragma unroll
;                 for (int q = 0; q < 2; ++q) {
;                     const f32x4 g4 = *(const f32x4*)(g + col + 4 * q), sh = *(const f32x4*)(mod + col + 4 * q), sc = *(const f32x4*)(mod + DM + col + 4 * q);
;                     const f32x4 h = (v[r][j][q] * rstd) * g4 * (sc + 1.0f) + sh;
;                     if (q == 0) { hw.x = cvt_pk_bf16(h[0], h[1]); hw.y = cvt_pk_bf16(h[2], h[3]); xw.x = cvt_pk_bf16(v[r][j][q][0], v[r][j][q][1]); xw.y = cvt_pk_bf16(v[r][j][q][2], v[r][j][q][3]); }
;                     else { hw.z = cvt_pk_bf16(h[0], h[1]); hw.w = cvt_pk_bf16(h[2], h[3]); xw.z = cvt_pk_bf16(v[r][j][q][0], v[r][j][q][1]); xw.w = cvt_pk_bf16(v[r][j][q][2], v[r][j][q][3]); }
;                 }
;                 *(u32x4*)(H + (size_t)row * DM + col) = hw;
	v_pk_mul_f32 v[148:149], v[20:21], v[148:149]
	v_pk_mul_f32 v[150:151], v[22:23], v[150:151]
	v_pk_mul_f32 v[152:153], v[24:25], v[152:153]
	v_pk_mul_f32 v[154:155], v[26:27], v[154:155]
	v_pk_mul_f32 v[156:157], v[28:29], v[156:157]
	v_pk_mul_f32 v[158:159], v[30:31], v[158:159]
	v_pk_fma_f32 v[144:145], v[48:49], v[144:145], v[32:33]
	v_pk_fma_f32 v[146:147], v[50:51], v[146:147], v[34:35]
	v_pk_fma_f32 v[148:149], v[52:53], v[148:149], v[36:37]
	v_pk_fma_f32 v[150:151], v[54:55], v[150:151], v[38:39]
	v_pk_fma_f32 v[152:153], v[56:57], v[152:153], v[40:41]
	v_pk_fma_f32 v[154:155], v[58:59], v[154:155], v[42:43]
	v_pk_fma_f32 v[156:157], v[60:61], v[156:157], v[44:45]
	v_pk_fma_f32 v[158:159], v[62:63], v[158:159], v[46:47]
	v_cvt_pk_bf16_f32 v184, v144, v145
	v_cvt_pk_bf16_f32 v185, v146, v147
	v_cvt_pk_bf16_f32 v186, v148, v149
	v_cvt_pk_bf16_f32 v187, v150, v151
	v_cvt_pk_bf16_f32 v188, v152, v153
	v_cvt_pk_bf16_f32 v189, v154, v155
	v_cvt_pk_bf16_f32 v190, v156, v157
	v_cvt_pk_bf16_f32 v191, v158, v159
	s_add_i32 s10, s98, 0x3
	s_lshl_b32 s10, s10, 11
	s_add_u32 s28, s26, s10
	s_addc_u32 s29, s27, 0
	global_store_dwordx4 v2, v[184:187], s[28:29] sc1
	global_store_dwordx4 v2, v[188:191], s[28:29] offset:1024 sc1
	s_add_i32 s10, s98, 0xa
	s_lshl_b32 s10, s10, 11
	s_add_u32 s28, s22, s10
	s_addc_u32 s29, s23, 0
	global_load_dwordx4 v[80:83], v2, s[28:29]
	global_load_dwordx4 v[84:87], v2, s[28:29] offset:1024
	s_add_i32 s10, s98, 0xb
	s_lshl_b32 s10, s10, 11
	s_add_u32 s28, s22, s10
	s_addc_u32 s29, s23, 0
	global_load_dwordx4 v[88:91], v2, s[28:29]
	global_load_dwordx4 v[92:95], v2, s[28:29] offset:1024
	s_waitcnt vmcnt(12)
	v_lshlrev_b32_e32 v128, 16, v96
	v_and_b32_e32 v129, 0xffff0000, v96
	v_lshlrev_b32_e32 v130, 16, v97
	v_and_b32_e32 v131, 0xffff0000, v97
	v_lshlrev_b32_e32 v132, 16, v98
	v_and_b32_e32 v133, 0xffff0000, v98
	v_lshlrev_b32_e32 v134, 16, v99
	v_and_b32_e32 v135, 0xffff0000, v99
	v_lshlrev_b32_e32 v136, 16, v100
	v_and_b32_e32 v137, 0xffff0000, v100
	v_lshlrev_b32_e32 v138, 16, v101
	v_and_b32_e32 v139, 0xffff0000, v101
	v_lshlrev_b32_e32 v140, 16, v102
	v_and_b32_e32 v141, 0xffff0000, v102
	v_lshlrev_b32_e32 v142, 16, v103
	v_and_b32_e32 v143, 0xffff0000, v103
	v_lshlrev_b32_e32 v144, 16, v104
	v_and_b32_e32 v145, 0xffff0000, v104
	v_lshlrev_b32_e32 v146, 16, v105
	v_and_b32_e32 v147, 0xffff0000, v105
	v_lshlrev_b32_e32 v148, 16, v106
	v_and_b32_e32 v149, 0xffff0000, v106
	v_lshlrev_b32_e32 v150, 16, v107
	v_and_b32_e32 v151, 0xffff0000, v107
	v_lshlrev_b32_e32 v152, 16, v108
	v_and_b32_e32 v153, 0xffff0000, v108
	v_lshlrev_b32_e32 v154, 16, v109
	v_and_b32_e32 v155, 0xffff0000, v109
	v_lshlrev_b32_e32 v156, 16, v110
	v_and_b32_e32 v157, 0xffff0000, v110
	v_lshlrev_b32_e32 v158, 16, v111
	v_and_b32_e32 v159, 0xffff0000, v111
	v_pk_mul_f32 v[160:161], v[128:129], v[128:129]
	v_pk_mul_f32 v[162:163], v[144:145], v[144:145]
	v_pk_fma_f32 v[160:161], v[130:131], v[130:131], v[160:161]
	v_pk_fma_f32 v[162:163], v[146:147], v[146:147], v[162:163]
	v_pk_fma_f32 v[160:161], v[132:133], v[132:133], v[160:161]
	v_pk_fma_f32 v[162:163], v[148:149], v[148:149], v[162:163]
	v_pk_fma_f32 v[160:161], v[134:135], v[134:135], v[160:161]
	v_pk_fma_f32 v[162:163], v[150:151], v[150:151], v[162:163]
	v_pk_fma_f32 v[160:161], v[136:137], v[136:137], v[160:161]
	v_pk_fma_f32 v[162:163], v[152:153], v[152:153], v[162:163]
	v_pk_fma_f32 v[160:161], v[138:139], v[138:139], v[160:161]
	v_pk_fma_f32 v[162:163], v[154:155], v[154:155], v[162:163]
	v_pk_fma_f32 v[160:161], v[140:141], v[140:141], v[160:161]
	v_pk_fma_f32 v[162:163], v[156:157], v[156:157], v[162:163]
	v_pk_fma_f32 v[160:161], v[142:143], v[142:143], v[160:161]
	v_pk_fma_f32 v[162:163], v[158:159], v[158:159], v[162:163]
	v_add_f32_e32 v160, v160, v161
	v_add_f32_e32 v162, v162, v163
	ds_bpermute_b32 v164, v5, v160
	ds_bpermute_b32 v165, v5, v162
	s_waitcnt lgkmcnt(0)
	v_add_f32_e32 v160, v160, v164
	v_add_f32_e32 v162, v162, v165
	ds_bpermute_b32 v164, v6, v160
	ds_bpermute_b32 v165, v6, v162
	s_waitcnt lgkmcnt(0)
	v_add_f32_e32 v160, v160, v164
	v_add_f32_e32 v162, v162, v165
	ds_bpermute_b32 v164, v7, v160
	ds_bpermute_b32 v165, v7, v162
	s_waitcnt lgkmcnt(0)
	v_add_f32_e32 v160, v160, v164
	v_add_f32_e32 v162, v162, v165
	ds_bpermute_b32 v164, v9, v160
	ds_bpermute_b32 v165, v9, v162
	s_waitcnt lgkmcnt(0)
	v_add_f32_e32 v160, v160, v164
	v_add_f32_e32 v162, v162, v165
	ds_bpermute_b32 v164, v10, v160
	ds_bpermute_b32 v165, v10, v162
	s_waitcnt lgkmcnt(0)
	v_add_f32_e32 v160, v160, v164
	v_add_f32_e32 v162, v162, v165
	ds_bpermute_b32 v164, v11, v160
	ds_bpermute_b32 v165, v11, v162
	s_waitcnt lgkmcnt(0)
; __device__ __forceinline__ unsigned cvt_pk_bf16(float lo, float hi) { unsigned r; asm volatile("v_cvt_pk_bf16_f32 %0, %1, %2" : "=v"(r) : "v"(lo), "v"(hi)); return r; }
; __device__ __forceinline__ void norm_phase(const Params& P, unsigned char* ws, int layer, int which, int nrows, bool first, int lane, int wave, const float* pend_part, int pend_ns, const float* pend_gate) {
;     ...
;             for (int j = 0; j < 2; ++j) { const int col = 8 * lane + 512 * j;
;                 if (first) { v[r][j][0] = *(const f32x4*)(P.in[I_X] + (size_t)row * DM + col); v[r][j][1] = *(const f32x4*)(P.in[I_X] + (size_t)row * DM + col + 4); }
;                 else { const u32x4 w = *(const u32x4*)(XB + (size_t)row * DM + col); v[r][j][0] = bf4_to_f32((u32x2){w.x, w.y}); v[r][j][1] = bf4_to_f32((u32x2){w.z, w.w}); } } }
; #pragma unroll
;         for (int r = 0; r < NR; ++r)
; #pragma unroll
;             for (int j = 0; j < 2; ++j)
; #pragma unroll
;                 for (int q = 0; q < 2; ++q) ss[r] += (v[r][j][q][0] * v[r][j][q][0] + v[r][j][q][1] * v[r][j][q][1]) + (v[r][j][q][2] * v[r][j][q][2] + v[r][j][q][3] * v[r][j][q][3]);
; #pragma unroll
;         for (int r = 0; r < NR; ++r) { const int row = row0 + r * NGW;
;             const float rstd = rsqrtf(wave_sum(ss[r], lane) * (1.0f / DM) + EPS);
;             const float* mod = (const float*)(ws + WS_MOD) + (size_t)(layer * 9 + (row >> 12)) * 6144 + which * 3 * DM;
; #pragma unroll
;             for (int j = 0; j < 2; ++j) { const int col = 8 * lane + 512 * j; u32x4 hw, xw;
; #pragma unroll
;                 for (int q = 0; q < 2; ++q) {
;                     const f32x4 g4 = *(const f32x4*)(g + col + 4 * q), sh = *(const f32x4*)(mod + col + 4 * q), sc = *(const f32x4*)(mod + DM + col + 4 * q);
;                     const f32x4 h = (v[r][j][q] * rstd) * g4 * (sc + 1.0f) + sh;
;                     if (q == 0) { hw.x = cvt_pk_bf16(h[0], h[1]); hw.y = cvt_pk_bf16(h[2], h[3]); xw.x = cvt_pk_bf16(v[r][j][q][0], v[r][j][q][1]); xw.y = cvt_pk_bf16(v[r][j][q][2], v[r][j][q][3]); }
;                     else { hw.z = cvt_pk_bf16(h[0], h[1]); hw.w = cvt_pk_bf16(h[2], h[3]); xw.z = cvt_pk_bf16(v[r][j][q][0], v[r][j][q][1]); xw.w = cvt_pk_bf16(v[r][j][q][2], v[r][j][q][3]); }
;                 }
;                 *(u32x4*)(H + (size_t)row * DM + col) = hw;
	v_add_f32_e32 v160, v160, v164
	v_add_f32_e32 v162, v162, v165
	v_fmamk_f32 v160, v160, 0x3a800000, v194
	v_fmamk_f32 v162, v162, 0x3a800000, v194
	v_rsq_f32_e32 v160, v160
	v_rsq_f32_e32 v162, v162
	s_nop 0
	v_pk_mul_f32 v[128:129], v[160:161], v[128:129] op_sel_hi:[0,1]
	v_pk_mul_f32 v[130:131], v[160:161], v[130:131] op_sel_hi:[0,1]
	v_pk_mul_f32 v[132:133], v[160:161], v[132:133] op_sel_hi:[0,1]
	v_pk_mul_f32 v[134:135], v[160:161], v[134:135] op_sel_hi:[0,1]
	v_pk_mul_f32 v[136:137], v[160:161], v[136:137] op_sel_hi:[0,1]
	v_pk_mul_f32 v[138:139], v[160:161], v[138:139] op_sel_hi:[0,1]
	v_pk_mul_f32 v[140:141], v[160:161], v[140:141] op_sel_hi:[0,1]
	v_pk_mul_f32 v[142:143], v[160:161], v[142:143] op_sel_hi:[0,1]
	v_pk_mul_f32 v[128:129], v[16:17], v[128:129]
	v_pk_mul_f32 v[130:131], v[18:19], v[130:131]
	v_pk_mul_f32 v[132:133], v[20:21], v[132:133]
	v_pk_mul_f32 v[134:135], v[22:23], v[134:135]
	v_pk_mul_f32 v[136:137], v[24:25], v[136:137]
	v_pk_mul_f32 v[138:139], v[26:27], v[138:139]
	v_pk_mul_f32 v[140:141], v[28:29], v[140:141]
	v_pk_mul_f32 v[142:143], v[30:31], v[142:143]
	v_pk_fma_f32 v[128:129], v[48:49], v[128:129], v[32:33]
	v_pk_fma_f32 v[130:131], v[50:51], v[130:131], v[34:35]
	v_pk_fma_f32 v[132:133], v[52:53], v[132:133], v[36:37]
	v_pk_fma_f32 v[134:135], v[54:55], v[134:135], v[38:39]
	v_pk_fma_f32 v[136:137], v[56:57], v[136:137], v[40:41]
	v_pk_fma_f32 v[138:139], v[58:59], v[138:139], v[42:43]
	v_pk_fma_f32 v[140:141], v[60:61], v[140:141], v[44:45]
	v_pk_fma_f32 v[142:143], v[62:63], v[142:143], v[46:47]
	v_cvt_pk_bf16_f32 v176, v128, v129
	v_cvt_pk_bf16_f32 v177, v130, v131
	v_cvt_pk_bf16_f32 v178, v132, v133
	v_cvt_pk_bf16_f32 v179, v134, v135
	v_cvt_pk_bf16_f32 v180, v136, v137
	v_cvt_pk_bf16_f32 v181, v138, v139
	v_cvt_pk_bf16_f32 v182, v140, v141
	v_cvt_pk_bf16_f32 v183, v142, v143
	s_add_i32 s10, s98, 0x4
	s_lshl_b32 s10, s10, 11
	s_add_u32 s28, s26, s10
	s_addc_u32 s29, s27, 0
	global_store_dwordx4 v2, v[176:179], s[28:29] sc1
	global_store_dwordx4 v2, v[180:183], s[28:29] offset:1024 sc1
	v_pk_mul_f32 v[144:145], v[162:163], v[144:145] op_sel_hi:[0,1]
	v_pk_mul_f32 v[146:147], v[162:163], v[146:147] op_sel_hi:[0,1]
	v_pk_mul_f32 v[148:149], v[162:163], v[148:149] op_sel_hi:[0,1]
	v_pk_mul_f32 v[150:151], v[162:163], v[150:151] op_sel_hi:[0,1]
	v_pk_mul_f32 v[152:153], v[162:163], v[152:153] op_sel_hi:[0,1]
	v_pk_mul_f32 v[154:155], v[162:163], v[154:155] op_sel_hi:[0,1]
	v_pk_mul_f32 v[156:157], v[162:163], v[156:157] op_sel_hi:[0,1]
	v_pk_mul_f32 v[158:159], v[162:163], v[158:159] op_sel_hi:[0,1]
	v_pk_mul_f32 v[144:145], v[16:17], v[144:145]
	v_pk_mul_f32 v[146:147], v[18:19], v[146:147]
	v_pk_mul_f32 v[148:149], v[20:21], v[148:149]
	v_pk_mul_f32 v[150:151], v[22:23], v[150:151]
	v_pk_mul_f32 v[152:153], v[24:25], v[152:153]
	v_pk_mul_f32 v[154:155], v[26:27], v[154:155]
	v_pk_mul_f32 v[156:157], v[28:29], v[156:157]
	v_pk_mul_f32 v[158:159], v[30:31], v[158:159]
	v_pk_fma_f32 v[144:145], v[48:49], v[144:145], v[32:33]
	v_pk_fma_f32 v[146:147], v[50:51], v[146:147], v[34:35]
	v_pk_fma_f32 v[148:149], v[52:53], v[148:149], v[36:37]
	v_pk_fma_f32 v[150:151], v[54:55], v[150:151], v[38:39]
	v_pk_fma_f32 v[152:153], v[56:57], v[152:153], v[40:41]
	v_pk_fma_f32 v[154:155], v[58:59], v[154:155], v[42:43]
	v_pk_fma_f32 v[156:157], v[60:61], v[156:157], v[44:45]
	v_pk_fma_f32 v[158:159], v[62:63], v[158:159], v[46:47]
	v_cvt_pk_bf16_f32 v184, v144, v145
	v_cvt_pk_bf16_f32 v185, v146, v147
	v_cvt_pk_bf16_f32 v186, v148, v149
	v_cvt_pk_bf16_f32 v187, v150, v151
	v_cvt_pk_bf16_f32 v188, v152, v153
	v_cvt_pk_bf16_f32 v189, v154, v155
	v_cvt_pk_bf16_f32 v190, v156, v157
	v_cvt_pk_bf16_f32 v191, v158, v159
	s_add_i32 s10, s98, 0x5
	s_lshl_b32 s10, s10, 11
	s_add_u32 s28, s26, s10
	s_addc_u32 s29, s27, 0
	global_store_dwordx4 v2, v[184:187], s[28:29] sc1
	global_store_dwordx4 v2, v[188:191], s[28:29] offset:1024 sc1
	s_add_i32 s10, s98, 0xc
	s_lshl_b32 s10, s10, 11
	s_add_u32 s28, s22, s10
	s_addc_u32 s29, s23, 0
	global_load_dwordx4 v[96:99], v2, s[28:29]
	global_load_dwordx4 v[100:103], v2, s[28:29] offset:1024
	s_add_i32 s10, s98, 0xd
	s_lshl_b32 s10, s10, 11
	s_add_u32 s28, s22, s10
	s_addc_u32 s29, s23, 0
	global_load_dwordx4 v[104:107], v2, s[28:29]
	global_load_dwordx4 v[108:111], v2, s[28:29] offset:1024
	s_waitcnt vmcnt(12)
	v_lshlrev_b32_e32 v128, 16, v112
	v_and_b32_e32 v129, 0xffff0000, v112
	v_lshlrev_b32_e32 v130, 16, v113
	v_and_b32_e32 v131, 0xffff0000, v113
	v_lshlrev_b32_e32 v132, 16, v114
	v_and_b32_e32 v133, 0xffff0000, v114
	v_lshlrev_b32_e32 v134, 16, v115
	v_and_b32_e32 v135, 0xffff0000, v115
	v_lshlrev_b32_e32 v136, 16, v116
	v_and_b32_e32 v137, 0xffff0000, v116
	v_lshlrev_b32_e32 v138, 16, v117
	v_and_b32_e32 v139, 0xffff0000, v117
	v_lshlrev_b32_e32 v140, 16, v118
	v_and_b32_e32 v141, 0xffff0000, v118
	v_lshlrev_b32_e32 v142, 16, v119
	v_and_b32_e32 v143, 0xffff0000, v119
	v_lshlrev_b32_e32 v144, 16, v120
	v_and_b32_e32 v145, 0xffff0000, v120
	v_lshlrev_b32_e32 v146, 16, v121
	v_and_b32_e32 v147, 0xffff0000, v121
	v_lshlrev_b32_e32 v148, 16, v122
	v_and_b32_e32 v149, 0xffff0000, v122
	v_lshlrev_b32_e32 v150, 16, v123
	v_and_b32_e32 v151, 0xffff0000, v123
	v_lshlrev_b32_e32 v152, 16, v124
	v_and_b32_e32 v153, 0xffff0000, v124
	v_lshlrev_b32_e32 v154, 16, v125
	v_and_b32_e32 v155, 0xffff0000, v125
	v_lshlrev_b32_e32 v156, 16, v126
	v_and_b32_e32 v157, 0xffff0000, v126
	v_lshlrev_b32_e32 v158, 16, v127
	v_and_b32_e32 v159, 0xffff0000, v127
	v_pk_mul_f32 v[160:161], v[128:129], v[128:129]
	v_pk_mul_f32 v[162:163], v[144:145], v[144:145]
	v_pk_fma_f32 v[160:161], v[130:131], v[130:131], v[160:161]
	v_pk_fma_f32 v[162:163], v[146:147], v[146:147], v[162:163]
	v_pk_fma_f32 v[160:161], v[132:133], v[132:133], v[160:161]
	v_pk_fma_f32 v[162:163], v[148:149], v[148:149], v[162:163]
	v_pk_fma_f32 v[160:161], v[134:135], v[134:135], v[160:161]
	v_pk_fma_f32 v[162:163], v[150:151], v[150:151], v[162:163]
	v_pk_fma_f32 v[160:161], v[136:137], v[136:137], v[160:161]
	v_pk_fma_f32 v[162:163], v[152:153], v[152:153], v[162:163]
	v_pk_fma_f32 v[160:161], v[138:139], v[138:139], v[160:161]
	v_pk_fma_f32 v[162:163], v[154:155], v[154:155], v[162:163]
	v_pk_fma_f32 v[160:161], v[140:141], v[140:141], v[160:161]
	v_pk_fma_f32 v[162:163], v[156:157], v[156:157], v[162:163]
	v_pk_fma_f32 v[160:161], v[142:143], v[142:143], v[160:161]
	v_pk_fma_f32 v[162:163], v[158:159], v[158:159], v[162:163]
	v_add_f32_e32 v160, v160, v161
	v_add_f32_e32 v162, v162, v163
	ds_bpermute_b32 v164, v5, v160
	ds_bpermute_b32 v165, v5, v162
	s_waitcnt lgkmcnt(0)
; __device__ __forceinline__ unsigned cvt_pk_bf16(float lo, float hi) { unsigned r; asm volatile("v_cvt_pk_bf16_f32 %0, %1, %2" : "=v"(r) : "v"(lo), "v"(hi)); return r; }
; __device__ __forceinline__ void norm_phase(const Params& P, unsigned char* ws, int layer, int which, int nrows, bool first, int lane, int wave, const float* pend_part, int pend_ns, const float* pend_gate) {
;     ...
;             for (int j = 0; j < 2; ++j) { const int col = 8 * lane + 512 * j;
;                 if (first) { v[r][j][0] = *(const f32x4*)(P.in[I_X] + (size_t)row * DM + col); v[r][j][1] = *(const f32x4*)(P.in[I_X] + (size_t)row * DM + col + 4); }
;                 else { const u32x4 w = *(const u32x4*)(XB + (size_t)row * DM + col); v[r][j][0] = bf4_to_f32((u32x2){w.x, w.y}); v[r][j][1] = bf4_to_f32((u32x2){w.z, w.w}); } } }
; #pragma unroll
;         for (int r = 0; r < NR; ++r)
; #pragma unroll
;             for (int j = 0; j < 2; ++j)
; #pragma unroll
;                 for (int q = 0; q < 2; ++q) ss[r] += (v[r][j][q][0] * v[r][j][q][0] + v[r][j][q][1] * v[r][j][q][1]) + (v[r][j][q][2] * v[r][j][q][2] + v[r][j][q][3] * v[r][j][q][3]);
; #pragma unroll
;         for (int r = 0; r < NR; ++r) { const int row = row0 + r * NGW;
;             const float rstd = rsqrtf(wave_sum(ss[r], lane) * (1.0f / DM) + EPS);
;             const float* mod = (const float*)(ws + WS_MOD) + (size_t)(layer * 9 + (row >> 12)) * 6144 + which * 3 * DM;
; #pragma unroll
;             for (int j = 0; j < 2; ++j) { const int col = 8 * lane + 512 * j; u32x4 hw, xw;
; #pragma unroll
;                 for (int q = 0; q < 2; ++q) {
;                     const f32x4 g4 = *(const f32x4*)(g + col + 4 * q), sh = *(const f32x4*)(mod + col + 4 * q), sc = *(const f32x4*)(mod + DM + col + 4 * q);
;                     const f32x4 h = (v[r][j][q] * rstd) * g4 * (sc + 1.0f) + sh;
;                     if (q == 0) { hw.x = cvt_pk_bf16(h[0], h[1]); hw.y = cvt_pk_bf16(h[2], h[3]); xw.x = cvt_pk_bf16(v[r][j][q][0], v[r][j][q][1]); xw.y = cvt_pk_bf16(v[r][j][q][2], v[r][j][q][3]); }
;                     else { hw.z = cvt_pk_bf16(h[0], h[1]); hw.w = cvt_pk_bf16(h[2], h[3]); xw.z = cvt_pk_bf16(v[r][j][q][0], v[r][j][q][1]); xw.w = cvt_pk_bf16(v[r][j][q][2], v[r][j][q][3]); }
;                 }
;                 *(u32x4*)(H + (size_t)row * DM + col) = hw;
	v_add_f32_e32 v160, v160, v164
	v_add_f32_e32 v162, v162, v165
	ds_bpermute_b32 v164, v6, v160
	ds_bpermute_b32 v165, v6, v162
	s_waitcnt lgkmcnt(0)
	v_add_f32_e32 v160, v160, v164
	v_add_f32_e32 v162, v162, v165
	ds_bpermute_b32 v164, v7, v160
	ds_bpermute_b32 v165, v7, v162
	s_waitcnt lgkmcnt(0)
	v_add_f32_e32 v160, v160, v164
	v_add_f32_e32 v162, v162, v165
	ds_bpermute_b32 v164, v9, v160
	ds_bpermute_b32 v165, v9, v162
	s_waitcnt lgkmcnt(0)
	v_add_f32_e32 v160, v160, v164
	v_add_f32_e32 v162, v162, v165
	ds_bpermute_b32 v164, v10, v160
	ds_bpermute_b32 v165, v10, v162
	s_waitcnt lgkmcnt(0)
	v_add_f32_e32 v160, v160, v164
	v_add_f32_e32 v162, v162, v165
	ds_bpermute_b32 v164, v11, v160
	ds_bpermute_b32 v165, v11, v162
	s_waitcnt lgkmcnt(0)
	v_add_f32_e32 v160, v160, v164
	v_add_f32_e32 v162, v162, v165
	v_fmamk_f32 v160, v160, 0x3a800000, v194
	v_fmamk_f32 v162, v162, 0x3a800000, v194
	v_rsq_f32_e32 v160, v160
	v_rsq_f32_e32 v162, v162
	s_nop 0
	v_pk_mul_f32 v[128:129], v[160:161], v[128:129] op_sel_hi:[0,1]
	v_pk_mul_f32 v[130:131], v[160:161], v[130:131] op_sel_hi:[0,1]
	v_pk_mul_f32 v[132:133], v[160:161], v[132:133] op_sel_hi:[0,1]
	v_pk_mul_f32 v[134:135], v[160:161], v[134:135] op_sel_hi:[0,1]
	v_pk_mul_f32 v[136:137], v[160:161], v[136:137] op_sel_hi:[0,1]
	v_pk_mul_f32 v[138:139], v[160:161], v[138:139] op_sel_hi:[0,1]
	v_pk_mul_f32 v[140:141], v[160:161], v[140:141] op_sel_hi:[0,1]
	v_pk_mul_f32 v[142:143], v[160:161], v[142:143] op_sel_hi:[0,1]
	v_pk_mul_f32 v[128:129], v[16:17], v[128:129]
	v_pk_mul_f32 v[130:131], v[18:19], v[130:131]
	v_pk_mul_f32 v[132:133], v[20:21], v[132:133]
	v_pk_mul_f32 v[134:135], v[22:23], v[134:135]
	v_pk_mul_f32 v[136:137], v[24:25], v[136:137]
	v_pk_mul_f32 v[138:139], v[26:27], v[138:139]
	v_pk_mul_f32 v[140:141], v[28:29], v[140:141]
	v_pk_mul_f32 v[142:143], v[30:31], v[142:143]
	v_pk_fma_f32 v[128:129], v[48:49], v[128:129], v[32:33]
	v_pk_fma_f32 v[130:131], v[50:51], v[130:131], v[34:35]
	v_pk_fma_f32 v[132:133], v[52:53], v[132:133], v[36:37]
	v_pk_fma_f32 v[134:135], v[54:55], v[134:135], v[38:39]
	v_pk_fma_f32 v[136:137], v[56:57], v[136:137], v[40:41]
	v_pk_fma_f32 v[138:139], v[58:59], v[138:139], v[42:43]
	v_pk_fma_f32 v[140:141], v[60:61], v[140:141], v[44:45]
	v_pk_fma_f32 v[142:143], v[62:63], v[142:143], v[46:47]
	v_cvt_pk_bf16_f32 v176, v128, v129
	v_cvt_pk_bf16_f32 v177, v130, v131
	v_cvt_pk_bf16_f32 v178, v132, v133
	v_cvt_pk_bf16_f32 v179, v134, v135
	v_cvt_pk_bf16_f32 v180, v136, v137
	v_cvt_pk_bf16_f32 v181, v138, v139
	v_cvt_pk_bf16_f32 v182, v140, v141
	v_cvt_pk_bf16_f32 v183, v142, v143
	s_add_i32 s10, s98, 0x6
	s_lshl_b32 s10, s10, 11
	s_add_u32 s28, s26, s10
	s_addc_u32 s29, s27, 0
	global_store_dwordx4 v2, v[176:179], s[28:29] sc1
	global_store_dwordx4 v2, v[180:183], s[28:29] offset:1024 sc1
	v_pk_mul_f32 v[144:145], v[162:163], v[144:145] op_sel_hi:[0,1]
	v_pk_mul_f32 v[146:147], v[162:163], v[146:147] op_sel_hi:[0,1]
	v_pk_mul_f32 v[148:149], v[162:163], v[148:149] op_sel_hi:[0,1]
	v_pk_mul_f32 v[150:151], v[162:163], v[150:151] op_sel_hi:[0,1]
	v_pk_mul_f32 v[152:153], v[162:163], v[152:153] op_sel_hi:[0,1]
	v_pk_mul_f32 v[154:155], v[162:163], v[154:155] op_sel_hi:[0,1]
	v_pk_mul_f32 v[156:157], v[162:163], v[156:157] op_sel_hi:[0,1]
	v_pk_mul_f32 v[158:159], v[162:163], v[158:159] op_sel_hi:[0,1]
	v_pk_mul_f32 v[144:145], v[16:17], v[144:145]
	v_pk_mul_f32 v[146:147], v[18:19], v[146:147]
	v_pk_mul_f32 v[148:149], v[20:21], v[148:149]
	v_pk_mul_f32 v[150:151], v[22:23], v[150:151]
	v_pk_mul_f32 v[152:153], v[24:25], v[152:153]
	v_pk_mul_f32 v[154:155], v[26:27], v[154:155]
	v_pk_mul_f32 v[156:157], v[28:29], v[156:157]
	v_pk_mul_f32 v[158:159], v[30:31], v[158:159]
	v_pk_fma_f32 v[144:145], v[48:49], v[144:145], v[32:33]
	v_pk_fma_f32 v[146:147], v[50:51], v[146:147], v[34:35]
	v_pk_fma_f32 v[148:149], v[52:53], v[148:149], v[36:37]
	v_pk_fma_f32 v[150:151], v[54:55], v[150:151], v[38:39]
	v_pk_fma_f32 v[152:153], v[56:57], v[152:153], v[40:41]
	v_pk_fma_f32 v[154:155], v[58:59], v[154:155], v[42:43]
	v_pk_fma_f32 v[156:157], v[60:61], v[156:157], v[44:45]
	v_pk_fma_f32 v[158:159], v[62:63], v[158:159], v[46:47]
	v_cvt_pk_bf16_f32 v184, v144, v145
	v_cvt_pk_bf16_f32 v185, v146, v147
	v_cvt_pk_bf16_f32 v186, v148, v149
	v_cvt_pk_bf16_f32 v187, v150, v151
	v_cvt_pk_bf16_f32 v188, v152, v153
	v_cvt_pk_bf16_f32 v189, v154, v155
	v_cvt_pk_bf16_f32 v190, v156, v157
	v_cvt_pk_bf16_f32 v191, v158, v159
	s_add_i32 s10, s98, 0x7
	s_lshl_b32 s10, s10, 11
	s_add_u32 s28, s26, s10
	s_addc_u32 s29, s27, 0
	global_store_dwordx4 v2, v[184:187], s[28:29] sc1
	global_store_dwordx4 v2, v[188:191], s[28:29] offset:1024 sc1
	s_add_i32 s10, s98, 0xe
	s_lshl_b32 s10, s10, 11
	s_add_u32 s28, s22, s10
	s_addc_u32 s29, s23, 0
	global_load_dwordx4 v[112:115], v2, s[28:29]
	global_load_dwordx4 v[116:119], v2, s[28:29] offset:1024
	s_add_i32 s10, s98, 0xf
	s_lshl_b32 s10, s10, 11
	s_add_u32 s28, s22, s10
	s_addc_u32 s29, s23, 0
	global_load_dwordx4 v[120:123], v2, s[28:29]
	global_load_dwordx4 v[124:127], v2, s[28:29] offset:1024
	s_waitcnt vmcnt(12)
; __device__ __forceinline__ unsigned cvt_pk_bf16(float lo, float hi) { unsigned r; asm volatile("v_cvt_pk_bf16_f32 %0, %1, %2" : "=v"(r) : "v"(lo), "v"(hi)); return r; }
; __device__ __forceinline__ void norm_phase(const Params& P, unsigned char* ws, int layer, int which, int nrows, bool first, int lane, int wave, const float* pend_part, int pend_ns, const float* pend_gate) {
;     ...
;             for (int j = 0; j < 2; ++j) { const int col = 8 * lane + 512 * j;
;                 if (first) { v[r][j][0] = *(const f32x4*)(P.in[I_X] + (size_t)row * DM + col); v[r][j][1] = *(const f32x4*)(P.in[I_X] + (size_t)row * DM + col + 4); }
;                 else { const u32x4 w = *(const u32x4*)(XB + (size_t)row * DM + col); v[r][j][0] = bf4_to_f32((u32x2){w.x, w.y}); v[r][j][1] = bf4_to_f32((u32x2){w.z, w.w}); } } }
; #pragma unroll
;         for (int r = 0; r < NR; ++r)
; #pragma unroll
;             for (int j = 0; j < 2; ++j)
; #pragma unroll
;                 for (int q = 0; q < 2; ++q) ss[r] += (v[r][j][q][0] * v[r][j][q][0] + v[r][j][q][1] * v[r][j][q][1]) + (v[r][j][q][2] * v[r][j][q][2] + v[r][j][q][3] * v[r][j][q][3]);
; #pragma unroll
;         for (int r = 0; r < NR; ++r) { const int row = row0 + r * NGW;
;             const float rstd = rsqrtf(wave_sum(ss[r], lane) * (1.0f / DM) + EPS);
;             const float* mod = (const float*)(ws + WS_MOD) + (size_t)(layer * 9 + (row >> 12)) * 6144 + which * 3 * DM;
; #pragma unroll
;             for (int j = 0; j < 2; ++j) { const int col = 8 * lane + 512 * j; u32x4 hw, xw;
; #pragma unroll
;                 for (int q = 0; q < 2; ++q) {
;                     const f32x4 g4 = *(const f32x4*)(g + col + 4 * q), sh = *(const f32x4*)(mod + col + 4 * q), sc = *(const f32x4*)(mod + DM + col + 4 * q);
;                     const f32x4 h = (v[r][j][q] * rstd) * g4 * (sc + 1.0f) + sh;
;                     if (q == 0) { hw.x = cvt_pk_bf16(h[0], h[1]); hw.y = cvt_pk_bf16(h[2], h[3]); xw.x = cvt_pk_bf16(v[r][j][q][0], v[r][j][q][1]); xw.y = cvt_pk_bf16(v[r][j][q][2], v[r][j][q][3]); }
;                     else { hw.z = cvt_pk_bf16(h[0], h[1]); hw.w = cvt_pk_bf16(h[2], h[3]); xw.z = cvt_pk_bf16(v[r][j][q][0], v[r][j][q][1]); xw.w = cvt_pk_bf16(v[r][j][q][2], v[r][j][q][3]); }
;                 }
;                 *(u32x4*)(H + (size_t)row * DM + col) = hw;
	v_lshlrev_b32_e32 v128, 16, v64
	v_and_b32_e32 v129, 0xffff0000, v64
	v_lshlrev_b32_e32 v130, 16, v65
	v_and_b32_e32 v131, 0xffff0000, v65
	v_lshlrev_b32_e32 v132, 16, v66
	v_and_b32_e32 v133, 0xffff0000, v66
	v_lshlrev_b32_e32 v134, 16, v67
	v_and_b32_e32 v135, 0xffff0000, v67
	v_lshlrev_b32_e32 v136, 16, v68
	v_and_b32_e32 v137, 0xffff0000, v68
	v_lshlrev_b32_e32 v138, 16, v69
	v_and_b32_e32 v139, 0xffff0000, v69
	v_lshlrev_b32_e32 v140, 16, v70
	v_and_b32_e32 v141, 0xffff0000, v70
	v_lshlrev_b32_e32 v142, 16, v71
	v_and_b32_e32 v143, 0xffff0000, v71
	v_lshlrev_b32_e32 v144, 16, v72
	v_and_b32_e32 v145, 0xffff0000, v72
	v_lshlrev_b32_e32 v146, 16, v73
	v_and_b32_e32 v147, 0xffff0000, v73
	v_lshlrev_b32_e32 v148, 16, v74
	v_and_b32_e32 v149, 0xffff0000, v74
	v_lshlrev_b32_e32 v150, 16, v75
	v_and_b32_e32 v151, 0xffff0000, v75
	v_lshlrev_b32_e32 v152, 16, v76
	v_and_b32_e32 v153, 0xffff0000, v76
	v_lshlrev_b32_e32 v154, 16, v77
	v_and_b32_e32 v155, 0xffff0000, v77
	v_lshlrev_b32_e32 v156, 16, v78
	v_and_b32_e32 v157, 0xffff0000, v78
	v_lshlrev_b32_e32 v158, 16, v79
	v_and_b32_e32 v159, 0xffff0000, v79
	v_pk_mul_f32 v[160:161], v[128:129], v[128:129]
	v_pk_mul_f32 v[162:163], v[144:145], v[144:145]
	v_pk_fma_f32 v[160:161], v[130:131], v[130:131], v[160:161]
	v_pk_fma_f32 v[162:163], v[146:147], v[146:147], v[162:163]
	v_pk_fma_f32 v[160:161], v[132:133], v[132:133], v[160:161]
	v_pk_fma_f32 v[162:163], v[148:149], v[148:149], v[162:163]
	v_pk_fma_f32 v[160:161], v[134:135], v[134:135], v[160:161]
	v_pk_fma_f32 v[162:163], v[150:151], v[150:151], v[162:163]
	v_pk_fma_f32 v[160:161], v[136:137], v[136:137], v[160:161]
	v_pk_fma_f32 v[162:163], v[152:153], v[152:153], v[162:163]
	v_pk_fma_f32 v[160:161], v[138:139], v[138:139], v[160:161]
	v_pk_fma_f32 v[162:163], v[154:155], v[154:155], v[162:163]
	v_pk_fma_f32 v[160:161], v[140:141], v[140:141], v[160:161]
	v_pk_fma_f32 v[162:163], v[156:157], v[156:157], v[162:163]
	v_pk_fma_f32 v[160:161], v[142:143], v[142:143], v[160:161]
	v_pk_fma_f32 v[162:163], v[158:159], v[158:159], v[162:163]
	v_add_f32_e32 v160, v160, v161
	v_add_f32_e32 v162, v162, v163
	ds_bpermute_b32 v164, v5, v160
	ds_bpermute_b32 v165, v5, v162
	s_waitcnt lgkmcnt(0)
	v_add_f32_e32 v160, v160, v164
	v_add_f32_e32 v162, v162, v165
	ds_bpermute_b32 v164, v6, v160
	ds_bpermute_b32 v165, v6, v162
	s_waitcnt lgkmcnt(0)
	v_add_f32_e32 v160, v160, v164
	v_add_f32_e32 v162, v162, v165
	ds_bpermute_b32 v164, v7, v160
	ds_bpermute_b32 v165, v7, v162
	s_waitcnt lgkmcnt(0)
	v_add_f32_e32 v160, v160, v164
	v_add_f32_e32 v162, v162, v165
	ds_bpermute_b32 v164, v9, v160
	ds_bpermute_b32 v165, v9, v162
	s_waitcnt lgkmcnt(0)
	v_add_f32_e32 v160, v160, v164
	v_add_f32_e32 v162, v162, v165
	ds_bpermute_b32 v164, v10, v160
	ds_bpermute_b32 v165, v10, v162
	s_waitcnt lgkmcnt(0)
	v_add_f32_e32 v160, v160, v164
	v_add_f32_e32 v162, v162, v165
	ds_bpermute_b32 v164, v11, v160
	ds_bpermute_b32 v165, v11, v162
	s_waitcnt lgkmcnt(0)
	v_add_f32_e32 v160, v160, v164
	v_add_f32_e32 v162, v162, v165
	v_fmamk_f32 v160, v160, 0x3a800000, v194
	v_fmamk_f32 v162, v162, 0x3a800000, v194
	v_rsq_f32_e32 v160, v160
	v_rsq_f32_e32 v162, v162
	s_nop 0
	v_pk_mul_f32 v[128:129], v[160:161], v[128:129] op_sel_hi:[0,1]
	v_pk_mul_f32 v[130:131], v[160:161], v[130:131] op_sel_hi:[0,1]
	v_pk_mul_f32 v[132:133], v[160:161], v[132:133] op_sel_hi:[0,1]
	v_pk_mul_f32 v[134:135], v[160:161], v[134:135] op_sel_hi:[0,1]
	v_pk_mul_f32 v[136:137], v[160:161], v[136:137] op_sel_hi:[0,1]
	v_pk_mul_f32 v[138:139], v[160:161], v[138:139] op_sel_hi:[0,1]
	v_pk_mul_f32 v[140:141], v[160:161], v[140:141] op_sel_hi:[0,1]
	v_pk_mul_f32 v[142:143], v[160:161], v[142:143] op_sel_hi:[0,1]
	v_pk_mul_f32 v[128:129], v[16:17], v[128:129]
	v_pk_mul_f32 v[130:131], v[18:19], v[130:131]
	v_pk_mul_f32 v[132:133], v[20:21], v[132:133]
	v_pk_mul_f32 v[134:135], v[22:23], v[134:135]
	v_pk_mul_f32 v[136:137], v[24:25], v[136:137]
	v_pk_mul_f32 v[138:139], v[26:27], v[138:139]
	v_pk_mul_f32 v[140:141], v[28:29], v[140:141]
	v_pk_mul_f32 v[142:143], v[30:31], v[142:143]
	v_pk_fma_f32 v[128:129], v[48:49], v[128:129], v[32:33]
	v_pk_fma_f32 v[130:131], v[50:51], v[130:131], v[34:35]
	v_pk_fma_f32 v[132:133], v[52:53], v[132:133], v[36:37]
	v_pk_fma_f32 v[134:135], v[54:55], v[134:135], v[38:39]
	v_pk_fma_f32 v[136:137], v[56:57], v[136:137], v[40:41]
	v_pk_fma_f32 v[138:139], v[58:59], v[138:139], v[42:43]
	v_pk_fma_f32 v[140:141], v[60:61], v[140:141], v[44:45]
	v_pk_fma_f32 v[142:143], v[62:63], v[142:143], v[46:47]
	v_cvt_pk_bf16_f32 v176, v128, v129
	v_cvt_pk_bf16_f32 v177, v130, v131
	v_cvt_pk_bf16_f32 v178, v132, v133
	v_cvt_pk_bf16_f32 v179, v134, v135
	v_cvt_pk_bf16_f32 v180, v136, v137
	v_cvt_pk_bf16_f32 v181, v138, v139
	v_cvt_pk_bf16_f32 v182, v140, v141
	v_cvt_pk_bf16_f32 v183, v142, v143
	s_add_i32 s10, s98, 0x8
	s_lshl_b32 s10, s10, 11
	s_add_u32 s28, s26, s10
	s_addc_u32 s29, s27, 0
	global_store_dwordx4 v2, v[176:179], s[28:29] sc1
	global_store_dwordx4 v2, v[180:183], s[28:29] offset:1024 sc1
	v_pk_mul_f32 v[144:145], v[162:163], v[144:145] op_sel_hi:[0,1]
	v_pk_mul_f32 v[146:147], v[162:163], v[146:147] op_sel_hi:[0,1]
	v_pk_mul_f32 v[148:149], v[162:163], v[148:149] op_sel_hi:[0,1]
	v_pk_mul_f32 v[150:151], v[162:163], v[150:151] op_sel_hi:[0,1]
	v_pk_mul_f32 v[152:153], v[162:163], v[152:153] op_sel_hi:[0,1]
	v_pk_mul_f32 v[154:155], v[162:163], v[154:155] op_sel_hi:[0,1]
	v_pk_mul_f32 v[156:157], v[162:163], v[156:157] op_sel_hi:[0,1]
	v_pk_mul_f32 v[158:159], v[162:163], v[158:159] op_sel_hi:[0,1]
	v_pk_mul_f32 v[144:145], v[16:17], v[144:145]
	v_pk_mul_f32 v[146:147], v[18:19], v[146:147]
	v_pk_mul_f32 v[148:149], v[20:21], v[148:149]
	v_pk_mul_f32 v[150:151], v[22:23], v[150:151]
	v_pk_mul_f32 v[152:153], v[24:25], v[152:153]
	v_pk_mul_f32 v[154:155], v[26:27], v[154:155]
	v_pk_mul_f32 v[156:157], v[28:29], v[156:157]
	v_pk_mul_f32 v[158:159], v[30:31], v[158:159]
	v_pk_fma_f32 v[144:145], v[48:49], v[144:145], v[32:33]
	v_pk_fma_f32 v[146:147], v[50:51], v[146:147], v[34:35]
	v_pk_fma_f32 v[148:149], v[52:53], v[148:149], v[36:37]
	v_pk_fma_f32 v[150:151], v[54:55], v[150:151], v[38:39]
	v_pk_fma_f32 v[152:153], v[56:57], v[152:153], v[40:41]
	v_pk_fma_f32 v[154:155], v[58:59], v[154:155], v[42:43]
	v_pk_fma_f32 v[156:157], v[60:61], v[156:157], v[44:45]
	v_pk_fma_f32 v[158:159], v[62:63], v[158:159], v[46:47]
	v_cvt_pk_bf16_f32 v184, v144, v145
	v_cvt_pk_bf16_f32 v185, v146, v147
	v_cvt_pk_bf16_f32 v186, v148, v149
	v_cvt_pk_bf16_f32 v187, v150, v151
	v_cvt_pk_bf16_f32 v188, v152, v153
	v_cvt_pk_bf16_f32 v189, v154, v155
	v_cvt_pk_bf16_f32 v190, v156, v157
	v_cvt_pk_bf16_f32 v191, v158, v159
	s_add_i32 s10, s98, 0x9
	s_lshl_b32 s10, s10, 11
	s_add_u32 s28, s26, s10
	s_addc_u32 s29, s27, 0
	global_store_dwordx4 v2, v[184:187], s[28:29] sc1
	global_store_dwordx4 v2, v[188:191], s[28:29] offset:1024 sc1
	s_waitcnt vmcnt(8)
; __device__ __forceinline__ unsigned cvt_pk_bf16(float lo, float hi) { unsigned r; asm volatile("v_cvt_pk_bf16_f32 %0, %1, %2" : "=v"(r) : "v"(lo), "v"(hi)); return r; }
; __device__ __forceinline__ void norm_phase(const Params& P, unsigned char* ws, int layer, int which, int nrows, bool first, int lane, int wave, const float* pend_part, int pend_ns, const float* pend_gate) {
;     ...
;             for (int j = 0; j < 2; ++j) { const int col = 8 * lane + 512 * j;
;                 if (first) { v[r][j][0] = *(const f32x4*)(P.in[I_X] + (size_t)row * DM + col); v[r][j][1] = *(const f32x4*)(P.in[I_X] + (size_t)row * DM + col + 4); }
;                 else { const u32x4 w = *(const u32x4*)(XB + (size_t)row * DM + col); v[r][j][0] = bf4_to_f32((u32x2){w.x, w.y}); v[r][j][1] = bf4_to_f32((u32x2){w.z, w.w}); } } }
; #pragma unroll
;         for (int r = 0; r < NR; ++r)
; #pragma unroll
;             for (int j = 0; j < 2; ++j)
; #pragma unroll
;                 for (int q = 0; q < 2; ++q) ss[r] += (v[r][j][q][0] * v[r][j][q][0] + v[r][j][q][1] * v[r][j][q][1]) + (v[r][j][q][2] * v[r][j][q][2] + v[r][j][q][3] * v[r][j][q][3]);
; #pragma unroll
;         for (int r = 0; r < NR; ++r) { const int row = row0 + r * NGW;
;             const float rstd = rsqrtf(wave_sum(ss[r], lane) * (1.0f / DM) + EPS);
;             const float* mod = (const float*)(ws + WS_MOD) + (size_t)(layer * 9 + (row >> 12)) * 6144 + which * 3 * DM;
; #pragma unroll
;             for (int j = 0; j < 2; ++j) { const int col = 8 * lane + 512 * j; u32x4 hw, xw;
; #pragma unroll
;                 for (int q = 0; q < 2; ++q) {
;                     const f32x4 g4 = *(const f32x4*)(g + col + 4 * q), sh = *(const f32x4*)(mod + col + 4 * q), sc = *(const f32x4*)(mod + DM + col + 4 * q);
;                     const f32x4 h = (v[r][j][q] * rstd) * g4 * (sc + 1.0f) + sh;
;                     if (q == 0) { hw.x = cvt_pk_bf16(h[0], h[1]); hw.y = cvt_pk_bf16(h[2], h[3]); xw.x = cvt_pk_bf16(v[r][j][q][0], v[r][j][q][1]); xw.y = cvt_pk_bf16(v[r][j][q][2], v[r][j][q][3]); }
;                     else { hw.z = cvt_pk_bf16(h[0], h[1]); hw.w = cvt_pk_bf16(h[2], h[3]); xw.z = cvt_pk_bf16(v[r][j][q][0], v[r][j][q][1]); xw.w = cvt_pk_bf16(v[r][j][q][2], v[r][j][q][3]); }
;                 }
;                 *(u32x4*)(H + (size_t)row * DM + col) = hw;
	v_lshlrev_b32_e32 v128, 16, v80
	v_and_b32_e32 v129, 0xffff0000, v80
	v_lshlrev_b32_e32 v130, 16, v81
	v_and_b32_e32 v131, 0xffff0000, v81
	v_lshlrev_b32_e32 v132, 16, v82
	v_and_b32_e32 v133, 0xffff0000, v82
	v_lshlrev_b32_e32 v134, 16, v83
	v_and_b32_e32 v135, 0xffff0000, v83
	v_lshlrev_b32_e32 v136, 16, v84
	v_and_b32_e32 v137, 0xffff0000, v84
	v_lshlrev_b32_e32 v138, 16, v85
	v_and_b32_e32 v139, 0xffff0000, v85
	v_lshlrev_b32_e32 v140, 16, v86
	v_and_b32_e32 v141, 0xffff0000, v86
	v_lshlrev_b32_e32 v142, 16, v87
	v_and_b32_e32 v143, 0xffff0000, v87
	v_lshlrev_b32_e32 v144, 16, v88
	v_and_b32_e32 v145, 0xffff0000, v88
	v_lshlrev_b32_e32 v146, 16, v89
	v_and_b32_e32 v147, 0xffff0000, v89
	v_lshlrev_b32_e32 v148, 16, v90
	v_and_b32_e32 v149, 0xffff0000, v90
	v_lshlrev_b32_e32 v150, 16, v91
	v_and_b32_e32 v151, 0xffff0000, v91
	v_lshlrev_b32_e32 v152, 16, v92
	v_and_b32_e32 v153, 0xffff0000, v92
	v_lshlrev_b32_e32 v154, 16, v93
	v_and_b32_e32 v155, 0xffff0000, v93
	v_lshlrev_b32_e32 v156, 16, v94
	v_and_b32_e32 v157, 0xffff0000, v94
	v_lshlrev_b32_e32 v158, 16, v95
	v_and_b32_e32 v159, 0xffff0000, v95
	v_pk_mul_f32 v[160:161], v[128:129], v[128:129]
	v_pk_mul_f32 v[162:163], v[144:145], v[144:145]
	v_pk_fma_f32 v[160:161], v[130:131], v[130:131], v[160:161]
	v_pk_fma_f32 v[162:163], v[146:147], v[146:147], v[162:163]
	v_pk_fma_f32 v[160:161], v[132:133], v[132:133], v[160:161]
	v_pk_fma_f32 v[162:163], v[148:149], v[148:149], v[162:163]
	v_pk_fma_f32 v[160:161], v[134:135], v[134:135], v[160:161]
	v_pk_fma_f32 v[162:163], v[150:151], v[150:151], v[162:163]
	v_pk_fma_f32 v[160:161], v[136:137], v[136:137], v[160:161]
	v_pk_fma_f32 v[162:163], v[152:153], v[152:153], v[162:163]
	v_pk_fma_f32 v[160:161], v[138:139], v[138:139], v[160:161]
	v_pk_fma_f32 v[162:163], v[154:155], v[154:155], v[162:163]
	v_pk_fma_f32 v[160:161], v[140:141], v[140:141], v[160:161]
	v_pk_fma_f32 v[162:163], v[156:157], v[156:157], v[162:163]
	v_pk_fma_f32 v[160:161], v[142:143], v[142:143], v[160:161]
	v_pk_fma_f32 v[162:163], v[158:159], v[158:159], v[162:163]
	v_add_f32_e32 v160, v160, v161
	v_add_f32_e32 v162, v162, v163
	ds_bpermute_b32 v164, v5, v160
	ds_bpermute_b32 v165, v5, v162
	s_waitcnt lgkmcnt(0)
	v_add_f32_e32 v160, v160, v164
	v_add_f32_e32 v162, v162, v165
	ds_bpermute_b32 v164, v6, v160
	ds_bpermute_b32 v165, v6, v162
	s_waitcnt lgkmcnt(0)
	v_add_f32_e32 v160, v160, v164
	v_add_f32_e32 v162, v162, v165
	ds_bpermute_b32 v164, v7, v160
	ds_bpermute_b32 v165, v7, v162
	s_waitcnt lgkmcnt(0)
	v_add_f32_e32 v160, v160, v164
	v_add_f32_e32 v162, v162, v165
	ds_bpermute_b32 v164, v9, v160
	ds_bpermute_b32 v165, v9, v162
	s_waitcnt lgkmcnt(0)
	v_add_f32_e32 v160, v160, v164
	v_add_f32_e32 v162, v162, v165
	ds_bpermute_b32 v164, v10, v160
	ds_bpermute_b32 v165, v10, v162
	s_waitcnt lgkmcnt(0)
	v_add_f32_e32 v160, v160, v164
	v_add_f32_e32 v162, v162, v165
	ds_bpermute_b32 v164, v11, v160
	ds_bpermute_b32 v165, v11, v162
	s_waitcnt lgkmcnt(0)
	v_add_f32_e32 v160, v160, v164
	v_add_f32_e32 v162, v162, v165
	v_fmamk_f32 v160, v160, 0x3a800000, v194
	v_fmamk_f32 v162, v162, 0x3a800000, v194
	v_rsq_f32_e32 v160, v160
	v_rsq_f32_e32 v162, v162
	s_nop 0
	v_pk_mul_f32 v[128:129], v[160:161], v[128:129] op_sel_hi:[0,1]
	v_pk_mul_f32 v[130:131], v[160:161], v[130:131] op_sel_hi:[0,1]
	v_pk_mul_f32 v[132:133], v[160:161], v[132:133] op_sel_hi:[0,1]
	v_pk_mul_f32 v[134:135], v[160:161], v[134:135] op_sel_hi:[0,1]
	v_pk_mul_f32 v[136:137], v[160:161], v[136:137] op_sel_hi:[0,1]
	v_pk_mul_f32 v[138:139], v[160:161], v[138:139] op_sel_hi:[0,1]
	v_pk_mul_f32 v[140:141], v[160:161], v[140:141] op_sel_hi:[0,1]
	v_pk_mul_f32 v[142:143], v[160:161], v[142:143] op_sel_hi:[0,1]
	v_pk_mul_f32 v[128:129], v[16:17], v[128:129]
	v_pk_mul_f32 v[130:131], v[18:19], v[130:131]
	v_pk_mul_f32 v[132:133], v[20:21], v[132:133]
	v_pk_mul_f32 v[134:135], v[22:23], v[134:135]
	v_pk_mul_f32 v[136:137], v[24:25], v[136:137]
	v_pk_mul_f32 v[138:139], v[26:27], v[138:139]
	v_pk_mul_f32 v[140:141], v[28:29], v[140:141]
	v_pk_mul_f32 v[142:143], v[30:31], v[142:143]
	v_pk_fma_f32 v[128:129], v[48:49], v[128:129], v[32:33]
	v_pk_fma_f32 v[130:131], v[50:51], v[130:131], v[34:35]
	v_pk_fma_f32 v[132:133], v[52:53], v[132:133], v[36:37]
	v_pk_fma_f32 v[134:135], v[54:55], v[134:135], v[38:39]
	v_pk_fma_f32 v[136:137], v[56:57], v[136:137], v[40:41]
	v_pk_fma_f32 v[138:139], v[58:59], v[138:139], v[42:43]
	v_pk_fma_f32 v[140:141], v[60:61], v[140:141], v[44:45]
	v_pk_fma_f32 v[142:143], v[62:63], v[142:143], v[46:47]
	v_cvt_pk_bf16_f32 v176, v128, v129
	v_cvt_pk_bf16_f32 v177, v130, v131
	v_cvt_pk_bf16_f32 v178, v132, v133
	v_cvt_pk_bf16_f32 v179, v134, v135
	v_cvt_pk_bf16_f32 v180, v136, v137
	v_cvt_pk_bf16_f32 v181, v138, v139
	v_cvt_pk_bf16_f32 v182, v140, v141
	v_cvt_pk_bf16_f32 v183, v142, v143
	s_add_i32 s10, s98, 0xa
	s_lshl_b32 s10, s10, 11
	s_add_u32 s28, s26, s10
	s_addc_u32 s29, s27, 0
	global_store_dwordx4 v2, v[176:179], s[28:29] sc1
	global_store_dwordx4 v2, v[180:183], s[28:29] offset:1024 sc1
	v_pk_mul_f32 v[144:145], v[162:163], v[144:145] op_sel_hi:[0,1]
	v_pk_mul_f32 v[146:147], v[162:163], v[146:147] op_sel_hi:[0,1]
	v_pk_mul_f32 v[148:149], v[162:163], v[148:149] op_sel_hi:[0,1]
	v_pk_mul_f32 v[150:151], v[162:163], v[150:151] op_sel_hi:[0,1]
	v_pk_mul_f32 v[152:153], v[162:163], v[152:153] op_sel_hi:[0,1]
	v_pk_mul_f32 v[154:155], v[162:163], v[154:155] op_sel_hi:[0,1]
	v_pk_mul_f32 v[156:157], v[162:163], v[156:157] op_sel_hi:[0,1]
	v_pk_mul_f32 v[158:159], v[162:163], v[158:159] op_sel_hi:[0,1]
	v_pk_mul_f32 v[144:145], v[16:17], v[144:145]
	v_pk_mul_f32 v[146:147], v[18:19], v[146:147]
	v_pk_mul_f32 v[148:149], v[20:21], v[148:149]
	v_pk_mul_f32 v[150:151], v[22:23], v[150:151]
	v_pk_mul_f32 v[152:153], v[24:25], v[152:153]
	v_pk_mul_f32 v[154:155], v[26:27], v[154:155]
	v_pk_mul_f32 v[156:157], v[28:29], v[156:157]
	v_pk_mul_f32 v[158:159], v[30:31], v[158:159]
	v_pk_fma_f32 v[144:145], v[48:49], v[144:145], v[32:33]
	v_pk_fma_f32 v[146:147], v[50:51], v[146:147], v[34:35]
	v_pk_fma_f32 v[148:149], v[52:53], v[148:149], v[36:37]
	v_pk_fma_f32 v[150:151], v[54:55], v[150:151], v[38:39]
	v_pk_fma_f32 v[152:153], v[56:57], v[152:153], v[40:41]
	v_pk_fma_f32 v[154:155], v[58:59], v[154:155], v[42:43]
	v_pk_fma_f32 v[156:157], v[60:61], v[156:157], v[44:45]
	v_pk_fma_f32 v[158:159], v[62:63], v[158:159], v[46:47]
	v_cvt_pk_bf16_f32 v184, v144, v145
	v_cvt_pk_bf16_f32 v185, v146, v147
	v_cvt_pk_bf16_f32 v186, v148, v149
	v_cvt_pk_bf16_f32 v187, v150, v151
	v_cvt_pk_bf16_f32 v188, v152, v153
	v_cvt_pk_bf16_f32 v189, v154, v155
	v_cvt_pk_bf16_f32 v190, v156, v157
	v_cvt_pk_bf16_f32 v191, v158, v159
	s_add_i32 s10, s98, 0xb
	s_lshl_b32 s10, s10, 11
	s_add_u32 s28, s26, s10
	s_addc_u32 s29, s27, 0
	global_store_dwordx4 v2, v[184:187], s[28:29] sc1
	global_store_dwordx4 v2, v[188:191], s[28:29] offset:1024 sc1
	s_waitcnt vmcnt(4)
; __device__ __forceinline__ unsigned cvt_pk_bf16(float lo, float hi) { unsigned r; asm volatile("v_cvt_pk_bf16_f32 %0, %1, %2" : "=v"(r) : "v"(lo), "v"(hi)); return r; }
; __device__ __forceinline__ void norm_phase(const Params& P, unsigned char* ws, int layer, int which, int nrows, bool first, int lane, int wave, const float* pend_part, int pend_ns, const float* pend_gate) {
;     ...
;             for (int j = 0; j < 2; ++j) { const int col = 8 * lane + 512 * j;
;                 if (first) { v[r][j][0] = *(const f32x4*)(P.in[I_X] + (size_t)row * DM + col); v[r][j][1] = *(const f32x4*)(P.in[I_X] + (size_t)row * DM + col + 4); }
;                 else { const u32x4 w = *(const u32x4*)(XB + (size_t)row * DM + col); v[r][j][0] = bf4_to_f32((u32x2){w.x, w.y}); v[r][j][1] = bf4_to_f32((u32x2){w.z, w.w}); } } }
; #pragma unroll
;         for (int r = 0; r < NR; ++r)
; #pragma unroll
;             for (int j = 0; j < 2; ++j)
; #pragma unroll
;                 for (int q = 0; q < 2; ++q) ss[r] += (v[r][j][q][0] * v[r][j][q][0] + v[r][j][q][1] * v[r][j][q][1]) + (v[r][j][q][2] * v[r][j][q][2] + v[r][j][q][3] * v[r][j][q][3]);
; #pragma unroll
;         for (int r = 0; r < NR; ++r) { const int row = row0 + r * NGW;
;             const float rstd = rsqrtf(wave_sum(ss[r], lane) * (1.0f / DM) + EPS);
;             const float* mod = (const float*)(ws + WS_MOD) + (size_t)(layer * 9 + (row >> 12)) * 6144 + which * 3 * DM;
; #pragma unroll
;             for (int j = 0; j < 2; ++j) { const int col = 8 * lane + 512 * j; u32x4 hw, xw;
; #pragma unroll
;                 for (int q = 0; q < 2; ++q) {
;                     const f32x4 g4 = *(const f32x4*)(g + col + 4 * q), sh = *(const f32x4*)(mod + col + 4 * q), sc = *(const f32x4*)(mod + DM + col + 4 * q);
;                     const f32x4 h = (v[r][j][q] * rstd) * g4 * (sc + 1.0f) + sh;
;                     if (q == 0) { hw.x = cvt_pk_bf16(h[0], h[1]); hw.y = cvt_pk_bf16(h[2], h[3]); xw.x = cvt_pk_bf16(v[r][j][q][0], v[r][j][q][1]); xw.y = cvt_pk_bf16(v[r][j][q][2], v[r][j][q][3]); }
;                     else { hw.z = cvt_pk_bf16(h[0], h[1]); hw.w = cvt_pk_bf16(h[2], h[3]); xw.z = cvt_pk_bf16(v[r][j][q][0], v[r][j][q][1]); xw.w = cvt_pk_bf16(v[r][j][q][2], v[r][j][q][3]); }
;                 }
;                 *(u32x4*)(H + (size_t)row * DM + col) = hw;
	v_lshlrev_b32_e32 v128, 16, v96
	v_and_b32_e32 v129, 0xffff0000, v96
	v_lshlrev_b32_e32 v130, 16, v97
	v_and_b32_e32 v131, 0xffff0000, v97
	v_lshlrev_b32_e32 v132, 16, v98
	v_and_b32_e32 v133, 0xffff0000, v98
	v_lshlrev_b32_e32 v134, 16, v99
	v_and_b32_e32 v135, 0xffff0000, v99
	v_lshlrev_b32_e32 v136, 16, v100
	v_and_b32_e32 v137, 0xffff0000, v100
	v_lshlrev_b32_e32 v138, 16, v101
	v_and_b32_e32 v139, 0xffff0000, v101
	v_lshlrev_b32_e32 v140, 16, v102
	v_and_b32_e32 v141, 0xffff0000, v102
	v_lshlrev_b32_e32 v142, 16, v103
	v_and_b32_e32 v143, 0xffff0000, v103
	v_lshlrev_b32_e32 v144, 16, v104
	v_and_b32_e32 v145, 0xffff0000, v104
	v_lshlrev_b32_e32 v146, 16, v105
	v_and_b32_e32 v147, 0xffff0000, v105
	v_lshlrev_b32_e32 v148, 16, v106
	v_and_b32_e32 v149, 0xffff0000, v106
	v_lshlrev_b32_e32 v150, 16, v107
	v_and_b32_e32 v151, 0xffff0000, v107
	v_lshlrev_b32_e32 v152, 16, v108
	v_and_b32_e32 v153, 0xffff0000, v108
	v_lshlrev_b32_e32 v154, 16, v109
	v_and_b32_e32 v155, 0xffff0000, v109
	v_lshlrev_b32_e32 v156, 16, v110
	v_and_b32_e32 v157, 0xffff0000, v110
	v_lshlrev_b32_e32 v158, 16, v111
	v_and_b32_e32 v159, 0xffff0000, v111
	v_pk_mul_f32 v[160:161], v[128:129], v[128:129]
	v_pk_mul_f32 v[162:163], v[144:145], v[144:145]
	v_pk_fma_f32 v[160:161], v[130:131], v[130:131], v[160:161]
	v_pk_fma_f32 v[162:163], v[146:147], v[146:147], v[162:163]
	v_pk_fma_f32 v[160:161], v[132:133], v[132:133], v[160:161]
	v_pk_fma_f32 v[162:163], v[148:149], v[148:149], v[162:163]
	v_pk_fma_f32 v[160:161], v[134:135], v[134:135], v[160:161]
	v_pk_fma_f32 v[162:163], v[150:151], v[150:151], v[162:163]
	v_pk_fma_f32 v[160:161], v[136:137], v[136:137], v[160:161]
	v_pk_fma_f32 v[162:163], v[152:153], v[152:153], v[162:163]
	v_pk_fma_f32 v[160:161], v[138:139], v[138:139], v[160:161]
	v_pk_fma_f32 v[162:163], v[154:155], v[154:155], v[162:163]
	v_pk_fma_f32 v[160:161], v[140:141], v[140:141], v[160:161]
	v_pk_fma_f32 v[162:163], v[156:157], v[156:157], v[162:163]
	v_pk_fma_f32 v[160:161], v[142:143], v[142:143], v[160:161]
	v_pk_fma_f32 v[162:163], v[158:159], v[158:159], v[162:163]
	v_add_f32_e32 v160, v160, v161
	v_add_f32_e32 v162, v162, v163
	ds_bpermute_b32 v164, v5, v160
	ds_bpermute_b32 v165, v5, v162
	s_waitcnt lgkmcnt(0)
	v_add_f32_e32 v160, v160, v164
	v_add_f32_e32 v162, v162, v165
	ds_bpermute_b32 v164, v6, v160
	ds_bpermute_b32 v165, v6, v162
	s_waitcnt lgkmcnt(0)
	v_add_f32_e32 v160, v160, v164
	v_add_f32_e32 v162, v162, v165
	ds_bpermute_b32 v164, v7, v160
	ds_bpermute_b32 v165, v7, v162
	s_waitcnt lgkmcnt(0)
	v_add_f32_e32 v160, v160, v164
	v_add_f32_e32 v162, v162, v165
	ds_bpermute_b32 v164, v9, v160
	ds_bpermute_b32 v165, v9, v162
	s_waitcnt lgkmcnt(0)
	v_add_f32_e32 v160, v160, v164
	v_add_f32_e32 v162, v162, v165
	ds_bpermute_b32 v164, v10, v160
	ds_bpermute_b32 v165, v10, v162
	s_waitcnt lgkmcnt(0)
	v_add_f32_e32 v160, v160, v164
	v_add_f32_e32 v162, v162, v165
	ds_bpermute_b32 v164, v11, v160
	ds_bpermute_b32 v165, v11, v162
	s_waitcnt lgkmcnt(0)
	v_add_f32_e32 v160, v160, v164
	v_add_f32_e32 v162, v162, v165
	v_fmamk_f32 v160, v160, 0x3a800000, v194
	v_fmamk_f32 v162, v162, 0x3a800000, v194
	v_rsq_f32_e32 v160, v160
	v_rsq_f32_e32 v162, v162
	s_nop 0
	v_pk_mul_f32 v[128:129], v[160:161], v[128:129] op_sel_hi:[0,1]
	v_pk_mul_f32 v[130:131], v[160:161], v[130:131] op_sel_hi:[0,1]
	v_pk_mul_f32 v[132:133], v[160:161], v[132:133] op_sel_hi:[0,1]
	v_pk_mul_f32 v[134:135], v[160:161], v[134:135] op_sel_hi:[0,1]
	v_pk_mul_f32 v[136:137], v[160:161], v[136:137] op_sel_hi:[0,1]
	v_pk_mul_f32 v[138:139], v[160:161], v[138:139] op_sel_hi:[0,1]
	v_pk_mul_f32 v[140:141], v[160:161], v[140:141] op_sel_hi:[0,1]
	v_pk_mul_f32 v[142:143], v[160:161], v[142:143] op_sel_hi:[0,1]
	v_pk_mul_f32 v[128:129], v[16:17], v[128:129]
	v_pk_mul_f32 v[130:131], v[18:19], v[130:131]
	v_pk_mul_f32 v[132:133], v[20:21], v[132:133]
	v_pk_mul_f32 v[134:135], v[22:23], v[134:135]
	v_pk_mul_f32 v[136:137], v[24:25], v[136:137]
	v_pk_mul_f32 v[138:139], v[26:27], v[138:139]
	v_pk_mul_f32 v[140:141], v[28:29], v[140:141]
	v_pk_mul_f32 v[142:143], v[30:31], v[142:143]
	v_pk_fma_f32 v[128:129], v[48:49], v[128:129], v[32:33]
	v_pk_fma_f32 v[130:131], v[50:51], v[130:131], v[34:35]
	v_pk_fma_f32 v[132:133], v[52:53], v[132:133], v[36:37]
	v_pk_fma_f32 v[134:135], v[54:55], v[134:135], v[38:39]
	v_pk_fma_f32 v[136:137], v[56:57], v[136:137], v[40:41]
	v_pk_fma_f32 v[138:139], v[58:59], v[138:139], v[42:43]
	v_pk_fma_f32 v[140:141], v[60:61], v[140:141], v[44:45]
	v_pk_fma_f32 v[142:143], v[62:63], v[142:143], v[46:47]
	v_cvt_pk_bf16_f32 v176, v128, v129
	v_cvt_pk_bf16_f32 v177, v130, v131
	v_cvt_pk_bf16_f32 v178, v132, v133
	v_cvt_pk_bf16_f32 v179, v134, v135
	v_cvt_pk_bf16_f32 v180, v136, v137
	v_cvt_pk_bf16_f32 v181, v138, v139
	v_cvt_pk_bf16_f32 v182, v140, v141
	v_cvt_pk_bf16_f32 v183, v142, v143
	s_add_i32 s10, s98, 0xc
	s_lshl_b32 s10, s10, 11
	s_add_u32 s28, s26, s10
	s_addc_u32 s29, s27, 0
	global_store_dwordx4 v2, v[176:179], s[28:29] sc1
	global_store_dwordx4 v2, v[180:183], s[28:29] offset:1024 sc1
	v_pk_mul_f32 v[144:145], v[162:163], v[144:145] op_sel_hi:[0,1]
	v_pk_mul_f32 v[146:147], v[162:163], v[146:147] op_sel_hi:[0,1]
	v_pk_mul_f32 v[148:149], v[162:163], v[148:149] op_sel_hi:[0,1]
	v_pk_mul_f32 v[150:151], v[162:163], v[150:151] op_sel_hi:[0,1]
	v_pk_mul_f32 v[152:153], v[162:163], v[152:153] op_sel_hi:[0,1]
	v_pk_mul_f32 v[154:155], v[162:163], v[154:155] op_sel_hi:[0,1]
	v_pk_mul_f32 v[156:157], v[162:163], v[156:157] op_sel_hi:[0,1]
	v_pk_mul_f32 v[158:159], v[162:163], v[158:159] op_sel_hi:[0,1]
	v_pk_mul_f32 v[144:145], v[16:17], v[144:145]
	v_pk_mul_f32 v[146:147], v[18:19], v[146:147]
	v_pk_mul_f32 v[148:149], v[20:21], v[148:149]
	v_pk_mul_f32 v[150:151], v[22:23], v[150:151]
	v_pk_mul_f32 v[152:153], v[24:25], v[152:153]
	v_pk_mul_f32 v[154:155], v[26:27], v[154:155]
	v_pk_mul_f32 v[156:157], v[28:29], v[156:157]
	v_pk_mul_f32 v[158:159], v[30:31], v[158:159]
	v_pk_fma_f32 v[144:145], v[48:49], v[144:145], v[32:33]
	v_pk_fma_f32 v[146:147], v[50:51], v[146:147], v[34:35]
	v_pk_fma_f32 v[148:149], v[52:53], v[148:149], v[36:37]
	v_pk_fma_f32 v[150:151], v[54:55], v[150:151], v[38:39]
	v_pk_fma_f32 v[152:153], v[56:57], v[152:153], v[40:41]
	v_pk_fma_f32 v[154:155], v[58:59], v[154:155], v[42:43]
	v_pk_fma_f32 v[156:157], v[60:61], v[156:157], v[44:45]
	v_pk_fma_f32 v[158:159], v[62:63], v[158:159], v[46:47]
	v_cvt_pk_bf16_f32 v184, v144, v145
	v_cvt_pk_bf16_f32 v185, v146, v147
	v_cvt_pk_bf16_f32 v186, v148, v149
	v_cvt_pk_bf16_f32 v187, v150, v151
	v_cvt_pk_bf16_f32 v188, v152, v153
	v_cvt_pk_bf16_f32 v189, v154, v155
	v_cvt_pk_bf16_f32 v190, v156, v157
	v_cvt_pk_bf16_f32 v191, v158, v159
	s_add_i32 s10, s98, 0xd
	s_lshl_b32 s10, s10, 11
	s_add_u32 s28, s26, s10
	s_addc_u32 s29, s27, 0
	global_store_dwordx4 v2, v[184:187], s[28:29] sc1
	global_store_dwordx4 v2, v[188:191], s[28:29] offset:1024 sc1
	s_waitcnt vmcnt(0)
; __device__ __forceinline__ void norm_phase(const Params& P, unsigned char* ws, int layer, int which, int nrows, bool first, int lane, int wave, const float* pend_part, int pend_ns, const float* pend_gate) {
;     ...
;             for (int j = 0; j < 2; ++j) { const int col = 8 * lane + 512 * j;
;                 if (first) { v[r][j][0] = *(const f32x4*)(P.in[I_X] + (size_t)row * DM + col); v[r][j][1] = *(const f32x4*)(P.in[I_X] + (size_t)row * DM + col + 4); }
;                 else { const u32x4 w = *(const u32x4*)(XB + (size_t)row * DM + col); v[r][j][0] = bf4_to_f32((u32x2){w.x, w.y}); v[r][j][1] = bf4_to_f32((u32x2){w.z, w.w}); } } }
; #pragma unroll
;         for (int r = 0; r < NR; ++r)
; #pragma unroll
;             for (int j = 0; j < 2; ++j)
; #pragma unroll
;                 for (int q = 0; q < 2; ++q) ss[r] += (v[r][j][q][0] * v[r][j][q][0] + v[r][j][q][1] * v[r][j][q][1]) + (v[r][j][q][2] * v[r][j][q][2] + v[r][j][q][3] * v[r][j][q][3]);
; #pragma unroll
;         for (int r = 0; r < NR; ++r) { const int row = row0 + r * NGW;
;             const float rstd = rsqrtf(wave_sum(ss[r], lane) * (1.0f / DM) + EPS);
;             const float* mod = (const float*)(ws + WS_MOD) + (size_t)(layer * 9 + (row >> 12)) * 6144 + which * 3 * DM;
; #pragma unroll
;             for (int j = 0; j < 2; ++j) { const int col = 8 * lane + 512 * j; u32x4 hw, xw;
; #pragma unroll
;                 for (int q = 0; q < 2; ++q) {
;                     const f32x4 g4 = *(const f32x4*)(g + col + 4 * q), sh = *(const f32x4*)(mod + col + 4 * q), sc = *(const f32x4*)(mod + DM + col + 4 * q);
;                     const f32x4 h = (v[r][j][q] * rstd) * g4 * (sc + 1.0f) + sh;
;                     if (q == 0) { hw.x = cvt_pk_bf16(h[0], h[1]); hw.y = cvt_pk_bf16(h[2], h[3]); xw.x = cvt_pk_bf16(v[r][j][q][0], v[r][j][q][1]); xw.y = cvt_pk_bf16(v[r][j][q][2], v[r][j][q][3]); }
;                     else { hw.z = cvt_pk_bf16(h[0], h[1]); hw.w = cvt_pk_bf16(h[2], h[3]); xw.z = cvt_pk_bf16(v[r][j][q][0], v[r][j][q][1]); xw.w = cvt_pk_bf16(v[r][j][q][2], v[r][j][q][3]); }
;                 }
;                 *(u32x4*)(H + (size_t)row * DM + col) = hw;
;                 if (first) *(u32x4*)(XB + (size_t)row * DM + col) = xw;
;             } }
	v_lshlrev_b32_e32 v128, 16, v112
	v_and_b32_e32 v129, 0xffff0000, v112
	v_lshlrev_b32_e32 v130, 16, v113
	v_and_b32_e32 v131, 0xffff0000, v113
	v_lshlrev_b32_e32 v132, 16, v114
	v_and_b32_e32 v133, 0xffff0000, v114
	v_lshlrev_b32_e32 v134, 16, v115
	v_and_b32_e32 v135, 0xffff0000, v115
	v_lshlrev_b32_e32 v136, 16, v116
	v_and_b32_e32 v137, 0xffff0000, v116
	v_lshlrev_b32_e32 v138, 16, v117
	v_and_b32_e32 v139, 0xffff0000, v117
	v_lshlrev_b32_e32 v140, 16, v118
	v_and_b32_e32 v141, 0xffff0000, v118
	v_lshlrev_b32_e32 v142, 16, v119
	v_and_b32_e32 v143, 0xffff0000, v119
	v_lshlrev_b32_e32 v144, 16, v120
	v_and_b32_e32 v145, 0xffff0000, v120
	v_lshlrev_b32_e32 v146, 16, v121
	v_and_b32_e32 v147, 0xffff0000, v121
	v_lshlrev_b32_e32 v148, 16, v122
	v_and_b32_e32 v149, 0xffff0000, v122
	v_lshlrev_b32_e32 v150, 16, v123
	v_and_b32_e32 v151, 0xffff0000, v123
	v_lshlrev_b32_e32 v152, 16, v124
	v_and_b32_e32 v153, 0xffff0000, v124
	v_lshlrev_b32_e32 v154, 16, v125
	v_and_b32_e32 v155, 0xffff0000, v125
	v_lshlrev_b32_e32 v156, 16, v126
	v_and_b32_e32 v157, 0xffff0000, v126
	v_lshlrev_b32_e32 v158, 16, v127
	v_and_b32_e32 v159, 0xffff0000, v127
	v_pk_mul_f32 v[160:161], v[128:129], v[128:129]
	v_pk_mul_f32 v[162:163], v[144:145], v[144:145]
	v_pk_fma_f32 v[160:161], v[130:131], v[130:131], v[160:161]
	v_pk_fma_f32 v[162:163], v[146:147], v[146:147], v[162:163]
	v_pk_fma_f32 v[160:161], v[132:133], v[132:133], v[160:161]
	v_pk_fma_f32 v[162:163], v[148:149], v[148:149], v[162:163]
	v_pk_fma_f32 v[160:161], v[134:135], v[134:135], v[160:161]
	v_pk_fma_f32 v[162:163], v[150:151], v[150:151], v[162:163]
	v_pk_fma_f32 v[160:161], v[136:137], v[136:137], v[160:161]
	v_pk_fma_f32 v[162:163], v[152:153], v[152:153], v[162:163]
	v_pk_fma_f32 v[160:161], v[138:139], v[138:139], v[160:161]
	v_pk_fma_f32 v[162:163], v[154:155], v[154:155], v[162:163]
	v_pk_fma_f32 v[160:161], v[140:141], v[140:141], v[160:161]
	v_pk_fma_f32 v[162:163], v[156:157], v[156:157], v[162:163]
	v_pk_fma_f32 v[160:161], v[142:143], v[142:143], v[160:161]
	v_pk_fma_f32 v[162:163], v[158:159], v[158:159], v[162:163]
	v_add_f32_e32 v160, v160, v161
	v_add_f32_e32 v162, v162, v163
	ds_bpermute_b32 v164, v5, v160
	ds_bpermute_b32 v165, v5, v162
	s_waitcnt lgkmcnt(0)
	v_add_f32_e32 v160, v160, v164
	v_add_f32_e32 v162, v162, v165
	ds_bpermute_b32 v164, v6, v160
	ds_bpermute_b32 v165, v6, v162
	s_waitcnt lgkmcnt(0)
	v_add_f32_e32 v160, v160, v164
	v_add_f32_e32 v162, v162, v165
	ds_bpermute_b32 v164, v7, v160
	ds_bpermute_b32 v165, v7, v162
	s_waitcnt lgkmcnt(0)
	v_add_f32_e32 v160, v160, v164
	v_add_f32_e32 v162, v162, v165
	ds_bpermute_b32 v164, v9, v160
	ds_bpermute_b32 v165, v9, v162
	s_waitcnt lgkmcnt(0)
	v_add_f32_e32 v160, v160, v164
	v_add_f32_e32 v162, v162, v165
	ds_bpermute_b32 v164, v10, v160
	ds_bpermute_b32 v165, v10, v162
	s_waitcnt lgkmcnt(0)
	v_add_f32_e32 v160, v160, v164
	v_add_f32_e32 v162, v162, v165
	ds_bpermute_b32 v164, v11, v160
	ds_bpermute_b32 v165, v11, v162
	s_waitcnt lgkmcnt(0)
	v_add_f32_e32 v160, v160, v164
	v_add_f32_e32 v162, v162, v165
	v_fmamk_f32 v160, v160, 0x3a800000, v194
	v_fmamk_f32 v162, v162, 0x3a800000, v194
	v_rsq_f32_e32 v160, v160
	v_rsq_f32_e32 v162, v162
	s_nop 0
	v_pk_mul_f32 v[128:129], v[160:161], v[128:129] op_sel_hi:[0,1]
	v_pk_mul_f32 v[130:131], v[160:161], v[130:131] op_sel_hi:[0,1]
	v_pk_mul_f32 v[132:133], v[160:161], v[132:133] op_sel_hi:[0,1]
	v_pk_mul_f32 v[134:135], v[160:161], v[134:135] op_sel_hi:[0,1]
	v_pk_mul_f32 v[136:137], v[160:161], v[136:137] op_sel_hi:[0,1]
	v_pk_mul_f32 v[138:139], v[160:161], v[138:139] op_sel_hi:[0,1]
	v_pk_mul_f32 v[140:141], v[160:161], v[140:141] op_sel_hi:[0,1]
	v_pk_mul_f32 v[142:143], v[160:161], v[142:143] op_sel_hi:[0,1]
	v_pk_mul_f32 v[128:129], v[16:17], v[128:129]
	v_pk_mul_f32 v[130:131], v[18:19], v[130:131]
	v_pk_mul_f32 v[132:133], v[20:21], v[132:133]
	v_pk_mul_f32 v[134:135], v[22:23], v[134:135]
	v_pk_mul_f32 v[136:137], v[24:25], v[136:137]
	v_pk_mul_f32 v[138:139], v[26:27], v[138:139]
	v_pk_mul_f32 v[140:141], v[28:29], v[140:141]
	v_pk_mul_f32 v[142:143], v[30:31], v[142:143]
	v_pk_fma_f32 v[128:129], v[48:49], v[128:129], v[32:33]
	v_pk_fma_f32 v[130:131], v[50:51], v[130:131], v[34:35]
	v_pk_fma_f32 v[132:133], v[52:53], v[132:133], v[36:37]
	v_pk_fma_f32 v[134:135], v[54:55], v[134:135], v[38:39]
	v_pk_fma_f32 v[136:137], v[56:57], v[136:137], v[40:41]
	v_pk_fma_f32 v[138:139], v[58:59], v[138:139], v[42:43]
	v_pk_fma_f32 v[140:141], v[60:61], v[140:141], v[44:45]
	v_pk_fma_f32 v[142:143], v[62:63], v[142:143], v[46:47]
	v_cvt_pk_bf16_f32 v176, v128, v129
	v_cvt_pk_bf16_f32 v177, v130, v131
	v_cvt_pk_bf16_f32 v178, v132, v133
	v_cvt_pk_bf16_f32 v179, v134, v135
	v_cvt_pk_bf16_f32 v180, v136, v137
	v_cvt_pk_bf16_f32 v181, v138, v139
	v_cvt_pk_bf16_f32 v182, v140, v141
	v_cvt_pk_bf16_f32 v183, v142, v143
	s_add_i32 s10, s98, 0xe
	s_lshl_b32 s10, s10, 11
	s_add_u32 s28, s26, s10
	s_addc_u32 s29, s27, 0
	global_store_dwordx4 v2, v[176:179], s[28:29] sc1
	global_store_dwordx4 v2, v[180:183], s[28:29] offset:1024 sc1
	v_pk_mul_f32 v[144:145], v[162:163], v[144:145] op_sel_hi:[0,1]
	v_pk_mul_f32 v[146:147], v[162:163], v[146:147] op_sel_hi:[0,1]
	v_pk_mul_f32 v[148:149], v[162:163], v[148:149] op_sel_hi:[0,1]
	v_pk_mul_f32 v[150:151], v[162:163], v[150:151] op_sel_hi:[0,1]
	v_pk_mul_f32 v[152:153], v[162:163], v[152:153] op_sel_hi:[0,1]
	v_pk_mul_f32 v[154:155], v[162:163], v[154:155] op_sel_hi:[0,1]
	v_pk_mul_f32 v[156:157], v[162:163], v[156:157] op_sel_hi:[0,1]
	v_pk_mul_f32 v[158:159], v[162:163], v[158:159] op_sel_hi:[0,1]
	v_pk_mul_f32 v[144:145], v[16:17], v[144:145]
	v_pk_mul_f32 v[146:147], v[18:19], v[146:147]
	v_pk_mul_f32 v[148:149], v[20:21], v[148:149]
	v_pk_mul_f32 v[150:151], v[22:23], v[150:151]
	v_pk_mul_f32 v[152:153], v[24:25], v[152:153]
	v_pk_mul_f32 v[154:155], v[26:27], v[154:155]
	v_pk_mul_f32 v[156:157], v[28:29], v[156:157]
	v_pk_mul_f32 v[158:159], v[30:31], v[158:159]
	v_pk_fma_f32 v[144:145], v[48:49], v[144:145], v[32:33]
	v_pk_fma_f32 v[146:147], v[50:51], v[146:147], v[34:35]
	v_pk_fma_f32 v[148:149], v[52:53], v[148:149], v[36:37]
	v_pk_fma_f32 v[150:151], v[54:55], v[150:151], v[38:39]
	v_pk_fma_f32 v[152:153], v[56:57], v[152:153], v[40:41]
	v_pk_fma_f32 v[154:155], v[58:59], v[154:155], v[42:43]
	v_pk_fma_f32 v[156:157], v[60:61], v[156:157], v[44:45]
	v_pk_fma_f32 v[158:159], v[62:63], v[158:159], v[46:47]
	v_cvt_pk_bf16_f32 v184, v144, v145
	v_cvt_pk_bf16_f32 v185, v146, v147
	v_cvt_pk_bf16_f32 v186, v148, v149
	v_cvt_pk_bf16_f32 v187, v150, v151
	v_cvt_pk_bf16_f32 v188, v152, v153
	v_cvt_pk_bf16_f32 v189, v154, v155
	v_cvt_pk_bf16_f32 v190, v156, v157
	v_cvt_pk_bf16_f32 v191, v158, v159
	s_add_i32 s10, s98, 0xf
	s_lshl_b32 s10, s10, 11
	s_add_u32 s28, s26, s10
	s_addc_u32 s29, s27, 0
	global_store_dwordx4 v2, v[184:187], s[28:29] sc1
	global_store_dwordx4 v2, v[188:191], s[28:29] offset:1024 sc1
	s_nop 1
	s_cmp_eq_u32 s99, 0
	s_cbranch_scc1 .LBB0_909
	s_branch .LBB0_951
